# P4 gate sigmoid: f32 reciprocal by v_rcp_f32 + one Newton-Raphson step (2 FMA) + v_div_fixup instead of the 12-instruction div_scale/div_fmas sequence (f32 throughout, 4 elements in lock-step); gates
# speedup vs baseline: 1.1649x; 1.0114x over previous
.Lp4f_gloop:
	s_waitcnt lgkmcnt(0)
	v_mfma_f32_32x32x16_bf16 v[50:65], v[232:235], v[220:223], v[50:65]
	v_xor_b32_e32 v240, 0x20, v250
	v_add_u32_e32 v228, v240, v248
	v_add_u32_e32 v240, v240, v249
	v_mfma_f32_32x32x16_bf16 v[34:49], v[236:239], v[220:223], v[34:49]
	ds_read_b128 v[220:223], v228
	ds_read_b128 v[228:231], v228 offset:4096
	v_mfma_f32_32x32x16_bf16 v[18:33], v[232:235], v[224:227], v[18:33]
	ds_read_b128 v[232:235], v240 offset:32768
	ds_read_b128 v[240:243], v240 offset:36864
	v_mfma_f32_32x32x16_bf16 v[2:17], v[236:239], v[224:227], v[2:17]
	s_waitcnt lgkmcnt(0)
	v_mfma_f32_32x32x16_bf16 v[50:65], v[232:235], v[220:223], v[50:65]
	v_xor_b32_e32 v236, 0x40, v250
	v_add_u32_e32 v224, v236, v248
	v_add_u32_e32 v236, v236, v249
	v_mfma_f32_32x32x16_bf16 v[34:49], v[240:243], v[220:223], v[34:49]
	ds_read_b128 v[220:223], v224
	ds_read_b128 v[224:227], v224 offset:4096
	v_mfma_f32_32x32x16_bf16 v[18:33], v[232:235], v[228:231], v[18:33]
	ds_read_b128 v[232:235], v236 offset:32768
	ds_read_b128 v[236:239], v236 offset:36864
	v_mfma_f32_32x32x16_bf16 v[2:17], v[240:243], v[228:231], v[2:17]
	s_waitcnt lgkmcnt(0)
	v_mfma_f32_32x32x16_bf16 v[50:65], v[232:235], v[220:223], v[50:65]
	v_xor_b32_e32 v240, 0x60, v250
	v_add_u32_e32 v228, v240, v248
	v_add_u32_e32 v240, v240, v249
	v_mfma_f32_32x32x16_bf16 v[34:49], v[236:239], v[220:223], v[34:49]
	ds_read_b128 v[220:223], v228
	ds_read_b128 v[228:231], v228 offset:4096
	v_mfma_f32_32x32x16_bf16 v[18:33], v[232:235], v[224:227], v[18:33]
	ds_read_b128 v[232:235], v240 offset:32768
	ds_read_b128 v[240:243], v240 offset:36864
	v_mfma_f32_32x32x16_bf16 v[2:17], v[236:239], v[224:227], v[2:17]
	s_waitcnt vmcnt(0) lgkmcnt(0)
	s_barrier
	s_waitcnt lgkmcnt(0)
	v_mfma_f32_32x32x16_bf16 v[50:65], v[232:235], v[220:223], v[50:65]
	v_mov_b32_e32 v236, v250
	v_add_u32_e32 v224, v236, v248
	v_add_u32_e32 v236, v236, v249
	v_mfma_f32_32x32x16_bf16 v[34:49], v[240:243], v[220:223], v[34:49]
	ds_read_b128 v[220:223], v224
	ds_read_b128 v[224:227], v224 offset:4096
	s_add_u32 m0, s30, 0x8000
	s_nop 0
	global_load_lds_dwordx4 v244, s[54:55]
	s_add_u32 m0, s30, 0x9000
	s_nop 0
	global_load_lds_dwordx4 v245, s[54:55]
	v_mfma_f32_32x32x16_bf16 v[18:33], v[232:235], v[228:231], v[18:33]
	ds_read_b128 v[232:235], v236 offset:49152
	ds_read_b128 v[236:239], v236 offset:53248
	s_add_u32 m0, s30, 0xa000
	s_nop 0
	global_load_lds_dwordx4 v246, s[54:55]
	s_add_u32 m0, s30, 0xb000
	s_nop 0
	global_load_lds_dwordx4 v247, s[54:55]
	v_mfma_f32_32x32x16_bf16 v[2:17], v[240:243], v[228:231], v[2:17]
	s_add_u32 s54, s54, 0x80
	s_addc_u32 s55, s55, 0
	s_waitcnt lgkmcnt(0)
	v_mfma_f32_32x32x16_bf16 v[114:129], v[232:235], v[220:223], v[114:129]
	v_xor_b32_e32 v240, 0x20, v250
	v_add_u32_e32 v228, v240, v248
	v_add_u32_e32 v240, v240, v249
	v_mfma_f32_32x32x16_bf16 v[98:113], v[236:239], v[220:223], v[98:113]
	ds_read_b128 v[220:223], v228
	ds_read_b128 v[228:231], v228 offset:4096
	v_mfma_f32_32x32x16_bf16 v[82:97], v[232:235], v[224:227], v[82:97]
	ds_read_b128 v[232:235], v240 offset:49152
	ds_read_b128 v[240:243], v240 offset:53248
	v_mfma_f32_32x32x16_bf16 v[66:81], v[236:239], v[224:227], v[66:81]
	s_waitcnt lgkmcnt(0)
	v_mfma_f32_32x32x16_bf16 v[114:129], v[232:235], v[220:223], v[114:129]
	v_xor_b32_e32 v236, 0x40, v250
	v_add_u32_e32 v224, v236, v248
	v_add_u32_e32 v236, v236, v249
	v_mfma_f32_32x32x16_bf16 v[98:113], v[240:243], v[220:223], v[98:113]
	ds_read_b128 v[220:223], v224
	ds_read_b128 v[224:227], v224 offset:4096
	v_mfma_f32_32x32x16_bf16 v[82:97], v[232:235], v[228:231], v[82:97]
	ds_read_b128 v[232:235], v236 offset:49152
	ds_read_b128 v[236:239], v236 offset:53248
	v_mfma_f32_32x32x16_bf16 v[66:81], v[240:243], v[228:231], v[66:81]
	s_waitcnt lgkmcnt(0)
	v_mfma_f32_32x32x16_bf16 v[114:129], v[232:235], v[220:223], v[114:129]
	v_xor_b32_e32 v240, 0x60, v250
	v_add_u32_e32 v228, v240, v248
	v_add_u32_e32 v240, v240, v249
	v_mfma_f32_32x32x16_bf16 v[98:113], v[236:239], v[220:223], v[98:113]
	ds_read_b128 v[220:223], v228
	ds_read_b128 v[228:231], v228 offset:4096
	v_mfma_f32_32x32x16_bf16 v[82:97], v[232:235], v[224:227], v[82:97]
	ds_read_b128 v[232:235], v240 offset:49152
	ds_read_b128 v[240:243], v240 offset:53248
	v_mfma_f32_32x32x16_bf16 v[66:81], v[236:239], v[224:227], v[66:81]
	s_waitcnt vmcnt(0) lgkmcnt(0)
	s_barrier
	s_waitcnt lgkmcnt(0)
	v_mfma_f32_32x32x16_bf16 v[114:129], v[232:235], v[220:223], v[114:129]
	v_mov_b32_e32 v236, v250
	v_add_u32_e32 v224, v236, v248
	v_add_u32_e32 v236, v236, v249
	v_mfma_f32_32x32x16_bf16 v[98:113], v[240:243], v[220:223], v[98:113]
	ds_read_b128 v[220:223], v224
	ds_read_b128 v[224:227], v224 offset:4096
	s_add_u32 m0, s30, 0xc000
	s_nop 0
	global_load_lds_dwordx4 v244, s[100:101]
	s_add_u32 m0, s30, 0xd000
	s_nop 0
	global_load_lds_dwordx4 v245, s[100:101]
	v_mfma_f32_32x32x16_bf16 v[82:97], v[232:235], v[228:231], v[82:97]
	ds_read_b128 v[232:235], v236 offset:32768
	ds_read_b128 v[236:239], v236 offset:36864
	s_add_u32 m0, s30, 0xe000
	s_nop 0
	global_load_lds_dwordx4 v246, s[100:101]
	s_add_u32 m0, s30, 0xf000
	s_nop 0
	global_load_lds_dwordx4 v247, s[100:101]
	v_mfma_f32_32x32x16_bf16 v[66:81], v[240:243], v[228:231], v[66:81]
	s_add_u32 s100, s100, 0x80
	s_addc_u32 s101, s101, 0
	s_waitcnt lgkmcnt(0)
	v_mfma_f32_32x32x16_bf16 v[178:193], v[232:235], v[220:223], v[178:193]
	v_xor_b32_e32 v240, 0x20, v250
	v_add_u32_e32 v228, v240, v248
	v_add_u32_e32 v240, v240, v249
	v_mfma_f32_32x32x16_bf16 v[162:177], v[236:239], v[220:223], v[162:177]
	ds_read_b128 v[220:223], v228
	ds_read_b128 v[228:231], v228 offset:4096
	v_mfma_f32_32x32x16_bf16 v[146:161], v[232:235], v[224:227], v[146:161]
	ds_read_b128 v[232:235], v240 offset:32768
	ds_read_b128 v[240:243], v240 offset:36864
	v_mfma_f32_32x32x16_bf16 v[130:145], v[236:239], v[224:227], v[130:145]
	s_waitcnt lgkmcnt(0)
	v_mfma_f32_32x32x16_bf16 v[178:193], v[232:235], v[220:223], v[178:193]
	v_xor_b32_e32 v236, 0x40, v250
	v_add_u32_e32 v224, v236, v248
	v_add_u32_e32 v236, v236, v249
	v_mfma_f32_32x32x16_bf16 v[162:177], v[240:243], v[220:223], v[162:177]
	ds_read_b128 v[220:223], v224
	ds_read_b128 v[224:227], v224 offset:4096
	v_mfma_f32_32x32x16_bf16 v[146:161], v[232:235], v[228:231], v[146:161]
	ds_read_b128 v[232:235], v236 offset:32768
	ds_read_b128 v[236:239], v236 offset:36864
	v_mfma_f32_32x32x16_bf16 v[130:145], v[240:243], v[228:231], v[130:145]
	s_waitcnt lgkmcnt(0)
	v_mfma_f32_32x32x16_bf16 v[178:193], v[232:235], v[220:223], v[178:193]
	v_xor_b32_e32 v240, 0x60, v250
	v_add_u32_e32 v228, v240, v248
	v_add_u32_e32 v240, v240, v249
	v_mfma_f32_32x32x16_bf16 v[162:177], v[236:239], v[220:223], v[162:177]
	ds_read_b128 v[220:223], v228
	ds_read_b128 v[228:231], v228 offset:4096
	v_mfma_f32_32x32x16_bf16 v[146:161], v[232:235], v[224:227], v[146:161]
	ds_read_b128 v[232:235], v240 offset:32768
	ds_read_b128 v[240:243], v240 offset:36864
	v_mfma_f32_32x32x16_bf16 v[130:145], v[236:239], v[224:227], v[130:145]
	s_waitcnt vmcnt(0) lgkmcnt(0)
	s_barrier
	s_waitcnt lgkmcnt(0)
	v_mfma_f32_32x32x16_bf16 v[178:193], v[232:235], v[220:223], v[178:193]
	v_mov_b32_e32 v236, v250
	v_add_u32_e32 v224, v236, v248
	v_add_u32_e32 v236, v236, v249
	v_mfma_f32_32x32x16_bf16 v[162:177], v[240:243], v[220:223], v[162:177]
	ds_read_b128 v[220:223], v224 offset:16384
	ds_read_b128 v[224:227], v224 offset:20480
	s_add_u32 m0, s30, 0x8000
	s_nop 0
	global_load_lds_dwordx4 v244, s[52:53]
	s_add_u32 m0, s30, 0x9000
	s_nop 0
	global_load_lds_dwordx4 v245, s[52:53]
	v_mfma_f32_32x32x16_bf16 v[146:161], v[232:235], v[228:231], v[146:161]
	ds_read_b128 v[232:235], v236 offset:49152
	ds_read_b128 v[236:239], v236 offset:53248
	s_add_u32 m0, s30, 0xa000
	s_nop 0
	global_load_lds_dwordx4 v246, s[52:53]
	s_add_u32 m0, s30, 0xb000
	s_nop 0
	global_load_lds_dwordx4 v247, s[52:53]
	v_mfma_f32_32x32x16_bf16 v[130:145], v[240:243], v[228:231], v[130:145]
	s_add_u32 m0, s30, 0x0
	s_nop 0
	global_load_lds_dwordx4 v244, s[98:99]
	s_add_u32 m0, s30, 0x1000
	s_nop 0
	global_load_lds_dwordx4 v245, s[98:99]
	s_add_u32 m0, s30, 0x2000
	s_nop 0
	global_load_lds_dwordx4 v246, s[98:99]
	s_add_u32 m0, s30, 0x3000
	s_nop 0
	global_load_lds_dwordx4 v247, s[98:99]
	s_add_u32 s52, s52, 0x80
	s_addc_u32 s53, s53, 0
	s_add_u32 s98, s98, 0x80
	s_addc_u32 s99, s99, 0
	s_waitcnt lgkmcnt(0)
	v_mfma_f32_32x32x16_bf16 v[50:65], v[232:235], v[220:223], v[50:65]
	v_xor_b32_e32 v240, 0x20, v250
	v_add_u32_e32 v228, v240, v248
	v_add_u32_e32 v240, v240, v249
	v_mfma_f32_32x32x16_bf16 v[34:49], v[236:239], v[220:223], v[34:49]
	ds_read_b128 v[220:223], v228 offset:16384
	ds_read_b128 v[228:231], v228 offset:20480
	v_mfma_f32_32x32x16_bf16 v[18:33], v[232:235], v[224:227], v[18:33]
	ds_read_b128 v[232:235], v240 offset:49152
	ds_read_b128 v[240:243], v240 offset:53248
	v_mfma_f32_32x32x16_bf16 v[2:17], v[236:239], v[224:227], v[2:17]
	s_waitcnt lgkmcnt(0)
	v_mfma_f32_32x32x16_bf16 v[50:65], v[232:235], v[220:223], v[50:65]
	v_xor_b32_e32 v236, 0x40, v250
	v_add_u32_e32 v224, v236, v248
	v_add_u32_e32 v236, v236, v249
	v_mfma_f32_32x32x16_bf16 v[34:49], v[240:243], v[220:223], v[34:49]
	ds_read_b128 v[220:223], v224 offset:16384
	ds_read_b128 v[224:227], v224 offset:20480
	v_mfma_f32_32x32x16_bf16 v[18:33], v[232:235], v[228:231], v[18:33]
	ds_read_b128 v[232:235], v236 offset:49152
	ds_read_b128 v[236:239], v236 offset:53248
	v_mfma_f32_32x32x16_bf16 v[2:17], v[240:243], v[228:231], v[2:17]
	s_waitcnt lgkmcnt(0)
	v_mfma_f32_32x32x16_bf16 v[50:65], v[232:235], v[220:223], v[50:65]
	v_xor_b32_e32 v240, 0x60, v250
	v_add_u32_e32 v228, v240, v248
	v_add_u32_e32 v240, v240, v249
	v_mfma_f32_32x32x16_bf16 v[34:49], v[236:239], v[220:223], v[34:49]
	ds_read_b128 v[220:223], v228 offset:16384
	ds_read_b128 v[228:231], v228 offset:20480
	v_mfma_f32_32x32x16_bf16 v[18:33], v[232:235], v[224:227], v[18:33]
	ds_read_b128 v[232:235], v240 offset:49152
	ds_read_b128 v[240:243], v240 offset:53248
	v_mfma_f32_32x32x16_bf16 v[2:17], v[236:239], v[224:227], v[2:17]
	s_waitcnt vmcnt(0) lgkmcnt(0)
	s_barrier
	s_waitcnt lgkmcnt(0)
	v_mfma_f32_32x32x16_bf16 v[50:65], v[232:235], v[220:223], v[50:65]
	v_mov_b32_e32 v236, v250
	v_add_u32_e32 v224, v236, v248
	v_add_u32_e32 v236, v236, v249
	v_mfma_f32_32x32x16_bf16 v[34:49], v[240:243], v[220:223], v[34:49]
	ds_read_b128 v[220:223], v224 offset:16384
	ds_read_b128 v[224:227], v224 offset:20480
	s_add_u32 m0, s30, 0xc000
	s_nop 0
	global_load_lds_dwordx4 v244, s[54:55]
	s_add_u32 m0, s30, 0xd000
	s_nop 0
	global_load_lds_dwordx4 v245, s[54:55]
	v_mfma_f32_32x32x16_bf16 v[18:33], v[232:235], v[228:231], v[18:33]
	ds_read_b128 v[232:235], v236 offset:32768
	ds_read_b128 v[236:239], v236 offset:36864
	s_add_u32 m0, s30, 0xe000
	s_nop 0
	global_load_lds_dwordx4 v246, s[54:55]
	s_add_u32 m0, s30, 0xf000
	s_nop 0
	global_load_lds_dwordx4 v247, s[54:55]
	v_mfma_f32_32x32x16_bf16 v[2:17], v[240:243], v[228:231], v[2:17]
	s_add_u32 s54, s54, 0x80
	s_addc_u32 s55, s55, 0
	s_waitcnt lgkmcnt(0)
	v_mfma_f32_32x32x16_bf16 v[114:129], v[232:235], v[220:223], v[114:129]
	v_xor_b32_e32 v240, 0x20, v250
	v_add_u32_e32 v228, v240, v248
	v_add_u32_e32 v240, v240, v249
	v_mfma_f32_32x32x16_bf16 v[98:113], v[236:239], v[220:223], v[98:113]
	ds_read_b128 v[220:223], v228 offset:16384
	ds_read_b128 v[228:231], v228 offset:20480
	v_mfma_f32_32x32x16_bf16 v[82:97], v[232:235], v[224:227], v[82:97]
	ds_read_b128 v[232:235], v240 offset:32768
	ds_read_b128 v[240:243], v240 offset:36864
	v_mfma_f32_32x32x16_bf16 v[66:81], v[236:239], v[224:227], v[66:81]
	s_waitcnt lgkmcnt(0)
	v_mfma_f32_32x32x16_bf16 v[114:129], v[232:235], v[220:223], v[114:129]
	v_xor_b32_e32 v236, 0x40, v250
	v_add_u32_e32 v224, v236, v248
	v_add_u32_e32 v236, v236, v249
	v_mfma_f32_32x32x16_bf16 v[98:113], v[240:243], v[220:223], v[98:113]
	ds_read_b128 v[220:223], v224 offset:16384
	ds_read_b128 v[224:227], v224 offset:20480
	v_mfma_f32_32x32x16_bf16 v[82:97], v[232:235], v[228:231], v[82:97]
	ds_read_b128 v[232:235], v236 offset:32768
	ds_read_b128 v[236:239], v236 offset:36864
	v_mfma_f32_32x32x16_bf16 v[66:81], v[240:243], v[228:231], v[66:81]
	s_waitcnt lgkmcnt(0)
	v_mfma_f32_32x32x16_bf16 v[114:129], v[232:235], v[220:223], v[114:129]
	v_xor_b32_e32 v240, 0x60, v250
	v_add_u32_e32 v228, v240, v248
	v_add_u32_e32 v240, v240, v249
	v_mfma_f32_32x32x16_bf16 v[98:113], v[236:239], v[220:223], v[98:113]
	ds_read_b128 v[220:223], v228 offset:16384
	ds_read_b128 v[228:231], v228 offset:20480
	v_mfma_f32_32x32x16_bf16 v[82:97], v[232:235], v[224:227], v[82:97]
	ds_read_b128 v[232:235], v240 offset:32768
	ds_read_b128 v[240:243], v240 offset:36864
	v_mfma_f32_32x32x16_bf16 v[66:81], v[236:239], v[224:227], v[66:81]
	s_waitcnt vmcnt(0) lgkmcnt(0)
	s_barrier
	s_waitcnt lgkmcnt(0)
	v_mfma_f32_32x32x16_bf16 v[114:129], v[232:235], v[220:223], v[114:129]
	v_mov_b32_e32 v236, v250
	v_add_u32_e32 v224, v236, v248
	v_add_u32_e32 v236, v236, v249
	v_mfma_f32_32x32x16_bf16 v[98:113], v[240:243], v[220:223], v[98:113]
	ds_read_b128 v[220:223], v224 offset:16384
	ds_read_b128 v[224:227], v224 offset:20480
	s_add_u32 m0, s30, 0x8000
	s_nop 0
	global_load_lds_dwordx4 v244, s[100:101]
	s_add_u32 m0, s30, 0x9000
	s_nop 0
	global_load_lds_dwordx4 v245, s[100:101]
	v_mfma_f32_32x32x16_bf16 v[82:97], v[232:235], v[228:231], v[82:97]
	ds_read_b128 v[232:235], v236 offset:49152
	ds_read_b128 v[236:239], v236 offset:53248
	s_add_u32 m0, s30, 0xa000
	s_nop 0
	global_load_lds_dwordx4 v246, s[100:101]
	s_add_u32 m0, s30, 0xb000
	s_nop 0
	global_load_lds_dwordx4 v247, s[100:101]
	v_mfma_f32_32x32x16_bf16 v[66:81], v[240:243], v[228:231], v[66:81]
	s_add_u32 s100, s100, 0x80
	s_addc_u32 s101, s101, 0
	s_waitcnt lgkmcnt(0)
	v_mfma_f32_32x32x16_bf16 v[178:193], v[232:235], v[220:223], v[178:193]
	v_xor_b32_e32 v240, 0x20, v250
	v_add_u32_e32 v228, v240, v248
	v_add_u32_e32 v240, v240, v249
	v_mfma_f32_32x32x16_bf16 v[162:177], v[236:239], v[220:223], v[162:177]
	ds_read_b128 v[220:223], v228 offset:16384
	ds_read_b128 v[228:231], v228 offset:20480
	v_mfma_f32_32x32x16_bf16 v[146:161], v[232:235], v[224:227], v[146:161]
	ds_read_b128 v[232:235], v240 offset:49152
	ds_read_b128 v[240:243], v240 offset:53248
	v_mfma_f32_32x32x16_bf16 v[130:145], v[236:239], v[224:227], v[130:145]
	s_waitcnt lgkmcnt(0)
	v_mfma_f32_32x32x16_bf16 v[178:193], v[232:235], v[220:223], v[178:193]
	v_xor_b32_e32 v236, 0x40, v250
	v_add_u32_e32 v224, v236, v248
	v_add_u32_e32 v236, v236, v249
	v_mfma_f32_32x32x16_bf16 v[162:177], v[240:243], v[220:223], v[162:177]
	ds_read_b128 v[220:223], v224 offset:16384
	ds_read_b128 v[224:227], v224 offset:20480
	v_mfma_f32_32x32x16_bf16 v[146:161], v[232:235], v[228:231], v[146:161]
	ds_read_b128 v[232:235], v236 offset:49152
	ds_read_b128 v[236:239], v236 offset:53248
	v_mfma_f32_32x32x16_bf16 v[130:145], v[240:243], v[228:231], v[130:145]
	s_waitcnt lgkmcnt(0)
	v_mfma_f32_32x32x16_bf16 v[178:193], v[232:235], v[220:223], v[178:193]
	v_xor_b32_e32 v240, 0x60, v250
	v_add_u32_e32 v228, v240, v248
	v_add_u32_e32 v240, v240, v249
	v_mfma_f32_32x32x16_bf16 v[162:177], v[236:239], v[220:223], v[162:177]
	ds_read_b128 v[220:223], v228 offset:16384
	ds_read_b128 v[228:231], v228 offset:20480
	v_mfma_f32_32x32x16_bf16 v[146:161], v[232:235], v[224:227], v[146:161]
	ds_read_b128 v[232:235], v240 offset:49152
	ds_read_b128 v[240:243], v240 offset:53248
	v_mfma_f32_32x32x16_bf16 v[130:145], v[236:239], v[224:227], v[130:145]
	s_waitcnt vmcnt(0) lgkmcnt(0)
	s_barrier
	s_waitcnt lgkmcnt(0)
	v_mfma_f32_32x32x16_bf16 v[178:193], v[232:235], v[220:223], v[178:193]
	v_mov_b32_e32 v236, v250
	v_add_u32_e32 v224, v236, v248
	v_add_u32_e32 v236, v236, v249
	v_mfma_f32_32x32x16_bf16 v[162:177], v[240:243], v[220:223], v[162:177]
	ds_read_b128 v[220:223], v224
	ds_read_b128 v[224:227], v224 offset:4096
	s_add_u32 m0, s30, 0xc000
	s_nop 0
	global_load_lds_dwordx4 v244, s[52:53]
	s_add_u32 m0, s30, 0xd000
	s_nop 0
	global_load_lds_dwordx4 v245, s[52:53]
	v_mfma_f32_32x32x16_bf16 v[146:161], v[232:235], v[228:231], v[146:161]
	ds_read_b128 v[232:235], v236 offset:32768
	ds_read_b128 v[236:239], v236 offset:36864
	s_add_u32 m0, s30, 0xe000
	s_nop 0
	global_load_lds_dwordx4 v246, s[52:53]
	s_add_u32 m0, s30, 0xf000
	s_nop 0
	global_load_lds_dwordx4 v247, s[52:53]
	v_mfma_f32_32x32x16_bf16 v[130:145], v[240:243], v[228:231], v[130:145]
	s_add_u32 m0, s30, 0x4000
	s_nop 0
	global_load_lds_dwordx4 v244, s[98:99]
	s_add_u32 m0, s30, 0x5000
	s_nop 0
	global_load_lds_dwordx4 v245, s[98:99]
	s_add_u32 m0, s30, 0x6000
	s_nop 0
	global_load_lds_dwordx4 v246, s[98:99]
	s_add_u32 m0, s30, 0x7000
	s_nop 0
	global_load_lds_dwordx4 v247, s[98:99]
	s_add_u32 s52, s52, 0x80
	s_addc_u32 s53, s53, 0
	s_add_u32 s98, s98, 0x80
	s_addc_u32 s99, s99, 0
	s_sub_u32 s51, s51, 1
	s_cmp_lg_u32 s51, 0
	s_cbranch_scc1 .Lp4f_gloop
	s_waitcnt lgkmcnt(0)
	v_mfma_f32_32x32x16_bf16 v[50:65], v[232:235], v[220:223], v[50:65]
	v_xor_b32_e32 v240, 0x20, v250
	v_add_u32_e32 v228, v240, v248
	v_add_u32_e32 v240, v240, v249
	v_mfma_f32_32x32x16_bf16 v[34:49], v[236:239], v[220:223], v[34:49]
	ds_read_b128 v[220:223], v228
	ds_read_b128 v[228:231], v228 offset:4096
	v_mfma_f32_32x32x16_bf16 v[18:33], v[232:235], v[224:227], v[18:33]
	ds_read_b128 v[232:235], v240 offset:32768
	ds_read_b128 v[240:243], v240 offset:36864
	v_mfma_f32_32x32x16_bf16 v[2:17], v[236:239], v[224:227], v[2:17]
	s_waitcnt lgkmcnt(0)
	v_mfma_f32_32x32x16_bf16 v[50:65], v[232:235], v[220:223], v[50:65]
	v_xor_b32_e32 v236, 0x40, v250
	v_add_u32_e32 v224, v236, v248
	v_add_u32_e32 v236, v236, v249
	v_mfma_f32_32x32x16_bf16 v[34:49], v[240:243], v[220:223], v[34:49]
	ds_read_b128 v[220:223], v224
	ds_read_b128 v[224:227], v224 offset:4096
	v_mfma_f32_32x32x16_bf16 v[18:33], v[232:235], v[228:231], v[18:33]
	ds_read_b128 v[232:235], v236 offset:32768
	ds_read_b128 v[236:239], v236 offset:36864
	v_mfma_f32_32x32x16_bf16 v[2:17], v[240:243], v[228:231], v[2:17]
	s_waitcnt lgkmcnt(0)
	v_mfma_f32_32x32x16_bf16 v[50:65], v[232:235], v[220:223], v[50:65]
	v_xor_b32_e32 v240, 0x60, v250
	v_add_u32_e32 v228, v240, v248
	v_add_u32_e32 v240, v240, v249
	v_mfma_f32_32x32x16_bf16 v[34:49], v[236:239], v[220:223], v[34:49]
	ds_read_b128 v[220:223], v228
	ds_read_b128 v[228:231], v228 offset:4096
	v_mfma_f32_32x32x16_bf16 v[18:33], v[232:235], v[224:227], v[18:33]
	ds_read_b128 v[232:235], v240 offset:32768
	ds_read_b128 v[240:243], v240 offset:36864
	v_mfma_f32_32x32x16_bf16 v[2:17], v[236:239], v[224:227], v[2:17]
	s_waitcnt vmcnt(0) lgkmcnt(0)
	s_barrier
	s_waitcnt lgkmcnt(0)
	v_mfma_f32_32x32x16_bf16 v[50:65], v[232:235], v[220:223], v[50:65]
	v_mov_b32_e32 v236, v250
	v_add_u32_e32 v224, v236, v248
	v_add_u32_e32 v236, v236, v249
	v_mfma_f32_32x32x16_bf16 v[34:49], v[240:243], v[220:223], v[34:49]
	ds_read_b128 v[220:223], v224
	ds_read_b128 v[224:227], v224 offset:4096
	s_add_u32 m0, s30, 0x8000
	s_nop 0
	global_load_lds_dwordx4 v244, s[54:55]
	s_add_u32 m0, s30, 0x9000
	s_nop 0
	global_load_lds_dwordx4 v245, s[54:55]
	v_mfma_f32_32x32x16_bf16 v[18:33], v[232:235], v[228:231], v[18:33]
	ds_read_b128 v[232:235], v236 offset:49152
	ds_read_b128 v[236:239], v236 offset:53248
	s_add_u32 m0, s30, 0xa000
	s_nop 0
	global_load_lds_dwordx4 v246, s[54:55]
	s_add_u32 m0, s30, 0xb000
	s_nop 0
	global_load_lds_dwordx4 v247, s[54:55]
	v_mfma_f32_32x32x16_bf16 v[2:17], v[240:243], v[228:231], v[2:17]
	s_add_u32 s54, s54, 0x80
	s_addc_u32 s55, s55, 0
	s_waitcnt lgkmcnt(0)
	v_mfma_f32_32x32x16_bf16 v[114:129], v[232:235], v[220:223], v[114:129]
	v_xor_b32_e32 v240, 0x20, v250
	v_add_u32_e32 v228, v240, v248
	v_add_u32_e32 v240, v240, v249
	v_mfma_f32_32x32x16_bf16 v[98:113], v[236:239], v[220:223], v[98:113]
	ds_read_b128 v[220:223], v228
	ds_read_b128 v[228:231], v228 offset:4096
	v_mfma_f32_32x32x16_bf16 v[82:97], v[232:235], v[224:227], v[82:97]
	ds_read_b128 v[232:235], v240 offset:49152
	ds_read_b128 v[240:243], v240 offset:53248
	v_mfma_f32_32x32x16_bf16 v[66:81], v[236:239], v[224:227], v[66:81]
	s_waitcnt lgkmcnt(0)
	v_mfma_f32_32x32x16_bf16 v[114:129], v[232:235], v[220:223], v[114:129]
	v_xor_b32_e32 v236, 0x40, v250
	v_add_u32_e32 v224, v236, v248
	v_add_u32_e32 v236, v236, v249
	v_mfma_f32_32x32x16_bf16 v[98:113], v[240:243], v[220:223], v[98:113]
	ds_read_b128 v[220:223], v224
	ds_read_b128 v[224:227], v224 offset:4096
	v_mfma_f32_32x32x16_bf16 v[82:97], v[232:235], v[228:231], v[82:97]
	ds_read_b128 v[232:235], v236 offset:49152
	ds_read_b128 v[236:239], v236 offset:53248
	v_mfma_f32_32x32x16_bf16 v[66:81], v[240:243], v[228:231], v[66:81]
	s_waitcnt lgkmcnt(0)
	v_mfma_f32_32x32x16_bf16 v[114:129], v[232:235], v[220:223], v[114:129]
	v_xor_b32_e32 v240, 0x60, v250
	v_add_u32_e32 v228, v240, v248
	v_add_u32_e32 v240, v240, v249
	v_mfma_f32_32x32x16_bf16 v[98:113], v[236:239], v[220:223], v[98:113]
	ds_read_b128 v[220:223], v228
	ds_read_b128 v[228:231], v228 offset:4096
	v_mfma_f32_32x32x16_bf16 v[82:97], v[232:235], v[224:227], v[82:97]
	ds_read_b128 v[232:235], v240 offset:49152
	ds_read_b128 v[240:243], v240 offset:53248
	v_mfma_f32_32x32x16_bf16 v[66:81], v[236:239], v[224:227], v[66:81]
	s_waitcnt vmcnt(0) lgkmcnt(0)
	s_barrier
	s_waitcnt lgkmcnt(0)
	v_mfma_f32_32x32x16_bf16 v[114:129], v[232:235], v[220:223], v[114:129]
	v_mov_b32_e32 v236, v250
	v_add_u32_e32 v224, v236, v248
	v_add_u32_e32 v236, v236, v249
	v_mfma_f32_32x32x16_bf16 v[98:113], v[240:243], v[220:223], v[98:113]
	ds_read_b128 v[220:223], v224
	ds_read_b128 v[224:227], v224 offset:4096
	s_add_u32 m0, s30, 0xc000
	s_nop 0
	global_load_lds_dwordx4 v244, s[100:101]
	s_add_u32 m0, s30, 0xd000
	s_nop 0
	global_load_lds_dwordx4 v245, s[100:101]
	v_mfma_f32_32x32x16_bf16 v[82:97], v[232:235], v[228:231], v[82:97]
	ds_read_b128 v[232:235], v236 offset:32768
	ds_read_b128 v[236:239], v236 offset:36864
	s_add_u32 m0, s30, 0xe000
	s_nop 0
	global_load_lds_dwordx4 v246, s[100:101]
	s_add_u32 m0, s30, 0xf000
	s_nop 0
	global_load_lds_dwordx4 v247, s[100:101]
	v_mfma_f32_32x32x16_bf16 v[66:81], v[240:243], v[228:231], v[66:81]
	s_add_u32 s100, s100, 0x80
	s_addc_u32 s101, s101, 0
	s_waitcnt lgkmcnt(0)
	v_mfma_f32_32x32x16_bf16 v[178:193], v[232:235], v[220:223], v[178:193]
	v_xor_b32_e32 v240, 0x20, v250
	v_add_u32_e32 v228, v240, v248
	v_add_u32_e32 v240, v240, v249
	v_mfma_f32_32x32x16_bf16 v[162:177], v[236:239], v[220:223], v[162:177]
	ds_read_b128 v[220:223], v228
	ds_read_b128 v[228:231], v228 offset:4096
	v_mfma_f32_32x32x16_bf16 v[146:161], v[232:235], v[224:227], v[146:161]
	ds_read_b128 v[232:235], v240 offset:32768
	ds_read_b128 v[240:243], v240 offset:36864
	v_mfma_f32_32x32x16_bf16 v[130:145], v[236:239], v[224:227], v[130:145]
	s_waitcnt lgkmcnt(0)
	v_mfma_f32_32x32x16_bf16 v[178:193], v[232:235], v[220:223], v[178:193]
	v_xor_b32_e32 v236, 0x40, v250
	v_add_u32_e32 v224, v236, v248
	v_add_u32_e32 v236, v236, v249
	v_mfma_f32_32x32x16_bf16 v[162:177], v[240:243], v[220:223], v[162:177]
	ds_read_b128 v[220:223], v224
	ds_read_b128 v[224:227], v224 offset:4096
	v_mfma_f32_32x32x16_bf16 v[146:161], v[232:235], v[228:231], v[146:161]
	ds_read_b128 v[232:235], v236 offset:32768
	ds_read_b128 v[236:239], v236 offset:36864
	v_mfma_f32_32x32x16_bf16 v[130:145], v[240:243], v[228:231], v[130:145]
	s_waitcnt lgkmcnt(0)
	v_mfma_f32_32x32x16_bf16 v[178:193], v[232:235], v[220:223], v[178:193]
	v_xor_b32_e32 v240, 0x60, v250
	v_add_u32_e32 v228, v240, v248
	v_add_u32_e32 v240, v240, v249
	v_mfma_f32_32x32x16_bf16 v[162:177], v[236:239], v[220:223], v[162:177]
	ds_read_b128 v[220:223], v228
	ds_read_b128 v[228:231], v228 offset:4096
	v_mfma_f32_32x32x16_bf16 v[146:161], v[232:235], v[224:227], v[146:161]
	ds_read_b128 v[232:235], v240 offset:32768
	ds_read_b128 v[240:243], v240 offset:36864
	v_mfma_f32_32x32x16_bf16 v[130:145], v[236:239], v[224:227], v[130:145]
	s_waitcnt vmcnt(0) lgkmcnt(0)
	s_barrier
	s_waitcnt lgkmcnt(0)
	v_mfma_f32_32x32x16_bf16 v[178:193], v[232:235], v[220:223], v[178:193]
	v_mov_b32_e32 v236, v250
	v_add_u32_e32 v224, v236, v248
	v_add_u32_e32 v236, v236, v249
	v_mfma_f32_32x32x16_bf16 v[162:177], v[240:243], v[220:223], v[162:177]
	ds_read_b128 v[220:223], v224 offset:16384
	ds_read_b128 v[224:227], v224 offset:20480
	s_add_u32 m0, s30, 0x8000
	s_nop 0
	global_load_lds_dwordx4 v244, s[52:53]
	s_add_u32 m0, s30, 0x9000
	s_nop 0
	global_load_lds_dwordx4 v245, s[52:53]
	v_mfma_f32_32x32x16_bf16 v[146:161], v[232:235], v[228:231], v[146:161]
	ds_read_b128 v[232:235], v236 offset:49152
	ds_read_b128 v[236:239], v236 offset:53248
	s_add_u32 m0, s30, 0xa000
	s_nop 0
	global_load_lds_dwordx4 v246, s[52:53]
	s_add_u32 m0, s30, 0xb000
	s_nop 0
	global_load_lds_dwordx4 v247, s[52:53]
	v_mfma_f32_32x32x16_bf16 v[130:145], v[240:243], v[228:231], v[130:145]
	s_add_u32 s52, s52, 0x80
	s_addc_u32 s53, s53, 0
	s_waitcnt lgkmcnt(0)
	v_mfma_f32_32x32x16_bf16 v[50:65], v[232:235], v[220:223], v[50:65]
	v_xor_b32_e32 v240, 0x20, v250
	v_add_u32_e32 v228, v240, v248
	v_add_u32_e32 v240, v240, v249
	v_mfma_f32_32x32x16_bf16 v[34:49], v[236:239], v[220:223], v[34:49]
	ds_read_b128 v[220:223], v228 offset:16384
	ds_read_b128 v[228:231], v228 offset:20480
	v_mfma_f32_32x32x16_bf16 v[18:33], v[232:235], v[224:227], v[18:33]
	ds_read_b128 v[232:235], v240 offset:49152
	ds_read_b128 v[240:243], v240 offset:53248
	v_mfma_f32_32x32x16_bf16 v[2:17], v[236:239], v[224:227], v[2:17]
	s_waitcnt lgkmcnt(0)
	v_mfma_f32_32x32x16_bf16 v[50:65], v[232:235], v[220:223], v[50:65]
	v_xor_b32_e32 v236, 0x40, v250
	v_add_u32_e32 v224, v236, v248
	v_add_u32_e32 v236, v236, v249
	v_mfma_f32_32x32x16_bf16 v[34:49], v[240:243], v[220:223], v[34:49]
	ds_read_b128 v[220:223], v224 offset:16384
	ds_read_b128 v[224:227], v224 offset:20480
	v_mfma_f32_32x32x16_bf16 v[18:33], v[232:235], v[228:231], v[18:33]
	ds_read_b128 v[232:235], v236 offset:49152
	ds_read_b128 v[236:239], v236 offset:53248
	v_mfma_f32_32x32x16_bf16 v[2:17], v[240:243], v[228:231], v[2:17]
	s_waitcnt lgkmcnt(0)
	v_mfma_f32_32x32x16_bf16 v[50:65], v[232:235], v[220:223], v[50:65]
	v_xor_b32_e32 v240, 0x60, v250
	v_add_u32_e32 v228, v240, v248
	v_add_u32_e32 v240, v240, v249
	v_mfma_f32_32x32x16_bf16 v[34:49], v[236:239], v[220:223], v[34:49]
	ds_read_b128 v[220:223], v228 offset:16384
	ds_read_b128 v[228:231], v228 offset:20480
	v_mfma_f32_32x32x16_bf16 v[18:33], v[232:235], v[224:227], v[18:33]
	ds_read_b128 v[232:235], v240 offset:49152
	ds_read_b128 v[240:243], v240 offset:53248
	v_mfma_f32_32x32x16_bf16 v[2:17], v[236:239], v[224:227], v[2:17]
	s_waitcnt vmcnt(0) lgkmcnt(0)
	s_barrier
	s_waitcnt lgkmcnt(0)
	v_mfma_f32_32x32x16_bf16 v[50:65], v[232:235], v[220:223], v[50:65]
	v_mov_b32_e32 v236, v250
	v_add_u32_e32 v224, v236, v248
	v_add_u32_e32 v236, v236, v249
	v_mfma_f32_32x32x16_bf16 v[34:49], v[240:243], v[220:223], v[34:49]
	ds_read_b128 v[220:223], v224 offset:16384
	ds_read_b128 v[224:227], v224 offset:20480
	s_add_u32 m0, s30, 0xc000
	s_nop 0
	global_load_lds_dwordx4 v244, s[54:55]
	s_add_u32 m0, s30, 0xd000
	s_nop 0
	global_load_lds_dwordx4 v245, s[54:55]
	v_mfma_f32_32x32x16_bf16 v[18:33], v[232:235], v[228:231], v[18:33]
	ds_read_b128 v[232:235], v236 offset:32768
	ds_read_b128 v[236:239], v236 offset:36864
	s_add_u32 m0, s30, 0xe000
	s_nop 0
	global_load_lds_dwordx4 v246, s[54:55]
	s_add_u32 m0, s30, 0xf000
	s_nop 0
	global_load_lds_dwordx4 v247, s[54:55]
	v_mfma_f32_32x32x16_bf16 v[2:17], v[240:243], v[228:231], v[2:17]
	s_add_u32 s54, s54, 0x80
	s_addc_u32 s55, s55, 0
	s_waitcnt lgkmcnt(0)
	v_mfma_f32_32x32x16_bf16 v[114:129], v[232:235], v[220:223], v[114:129]
	v_xor_b32_e32 v240, 0x20, v250
	v_add_u32_e32 v228, v240, v248
	v_add_u32_e32 v240, v240, v249
	v_mfma_f32_32x32x16_bf16 v[98:113], v[236:239], v[220:223], v[98:113]
	ds_read_b128 v[220:223], v228 offset:16384
	ds_read_b128 v[228:231], v228 offset:20480
	v_mfma_f32_32x32x16_bf16 v[82:97], v[232:235], v[224:227], v[82:97]
	ds_read_b128 v[232:235], v240 offset:32768
	ds_read_b128 v[240:243], v240 offset:36864
	v_mfma_f32_32x32x16_bf16 v[66:81], v[236:239], v[224:227], v[66:81]
	s_waitcnt lgkmcnt(0)
	v_mfma_f32_32x32x16_bf16 v[114:129], v[232:235], v[220:223], v[114:129]
	v_xor_b32_e32 v236, 0x40, v250
	v_add_u32_e32 v224, v236, v248
	v_add_u32_e32 v236, v236, v249
	v_mfma_f32_32x32x16_bf16 v[98:113], v[240:243], v[220:223], v[98:113]
	ds_read_b128 v[220:223], v224 offset:16384
	ds_read_b128 v[224:227], v224 offset:20480
	v_mfma_f32_32x32x16_bf16 v[82:97], v[232:235], v[228:231], v[82:97]
	ds_read_b128 v[232:235], v236 offset:32768
	ds_read_b128 v[236:239], v236 offset:36864
	v_mfma_f32_32x32x16_bf16 v[66:81], v[240:243], v[228:231], v[66:81]
	s_waitcnt lgkmcnt(0)
	v_mfma_f32_32x32x16_bf16 v[114:129], v[232:235], v[220:223], v[114:129]
	v_xor_b32_e32 v240, 0x60, v250
	v_add_u32_e32 v228, v240, v248
	v_add_u32_e32 v240, v240, v249
	v_mfma_f32_32x32x16_bf16 v[98:113], v[236:239], v[220:223], v[98:113]
	ds_read_b128 v[220:223], v228 offset:16384
	ds_read_b128 v[228:231], v228 offset:20480
	v_mfma_f32_32x32x16_bf16 v[82:97], v[232:235], v[224:227], v[82:97]
	ds_read_b128 v[232:235], v240 offset:32768
	ds_read_b128 v[240:243], v240 offset:36864
	v_mfma_f32_32x32x16_bf16 v[66:81], v[236:239], v[224:227], v[66:81]
	s_waitcnt vmcnt(0) lgkmcnt(0)
	s_barrier
	s_waitcnt lgkmcnt(0)
	v_mfma_f32_32x32x16_bf16 v[114:129], v[232:235], v[220:223], v[114:129]
	v_mov_b32_e32 v236, v250
	v_add_u32_e32 v224, v236, v248
	v_add_u32_e32 v236, v236, v249
	v_mfma_f32_32x32x16_bf16 v[98:113], v[240:243], v[220:223], v[98:113]
	ds_read_b128 v[220:223], v224 offset:16384
	ds_read_b128 v[224:227], v224 offset:20480
	v_mfma_f32_32x32x16_bf16 v[82:97], v[232:235], v[228:231], v[82:97]
	ds_read_b128 v[232:235], v236 offset:49152
	ds_read_b128 v[236:239], v236 offset:53248
	v_mfma_f32_32x32x16_bf16 v[66:81], v[240:243], v[228:231], v[66:81]
	s_waitcnt lgkmcnt(0)
	v_mfma_f32_32x32x16_bf16 v[178:193], v[232:235], v[220:223], v[178:193]
	v_xor_b32_e32 v240, 0x20, v250
	v_add_u32_e32 v228, v240, v248
	v_add_u32_e32 v240, v240, v249
	v_mfma_f32_32x32x16_bf16 v[162:177], v[236:239], v[220:223], v[162:177]
	ds_read_b128 v[220:223], v228 offset:16384
	ds_read_b128 v[228:231], v228 offset:20480
	v_mfma_f32_32x32x16_bf16 v[146:161], v[232:235], v[224:227], v[146:161]
	ds_read_b128 v[232:235], v240 offset:49152
	ds_read_b128 v[240:243], v240 offset:53248
	v_mfma_f32_32x32x16_bf16 v[130:145], v[236:239], v[224:227], v[130:145]
	s_waitcnt lgkmcnt(0)
	v_mfma_f32_32x32x16_bf16 v[178:193], v[232:235], v[220:223], v[178:193]
	v_xor_b32_e32 v236, 0x40, v250
	v_add_u32_e32 v224, v236, v248
	v_add_u32_e32 v236, v236, v249
	v_mfma_f32_32x32x16_bf16 v[162:177], v[240:243], v[220:223], v[162:177]
	ds_read_b128 v[220:223], v224 offset:16384
	ds_read_b128 v[224:227], v224 offset:20480
	v_mfma_f32_32x32x16_bf16 v[146:161], v[232:235], v[228:231], v[146:161]
	ds_read_b128 v[232:235], v236 offset:49152
	ds_read_b128 v[236:239], v236 offset:53248
	v_mfma_f32_32x32x16_bf16 v[130:145], v[240:243], v[228:231], v[130:145]
	s_waitcnt lgkmcnt(0)
	v_mfma_f32_32x32x16_bf16 v[178:193], v[232:235], v[220:223], v[178:193]
	v_xor_b32_e32 v240, 0x60, v250
	v_add_u32_e32 v228, v240, v248
	v_add_u32_e32 v240, v240, v249
	v_mfma_f32_32x32x16_bf16 v[162:177], v[236:239], v[220:223], v[162:177]
	ds_read_b128 v[220:223], v228 offset:16384
	ds_read_b128 v[228:231], v228 offset:20480
	v_mfma_f32_32x32x16_bf16 v[146:161], v[232:235], v[224:227], v[146:161]
	ds_read_b128 v[232:235], v240 offset:49152
	ds_read_b128 v[240:243], v240 offset:53248
	v_mfma_f32_32x32x16_bf16 v[130:145], v[236:239], v[224:227], v[130:145]
	s_waitcnt lgkmcnt(0)
	v_mfma_f32_32x32x16_bf16 v[178:193], v[232:235], v[220:223], v[178:193]
	v_mfma_f32_32x32x16_bf16 v[162:177], v[240:243], v[220:223], v[162:177]
	v_mfma_f32_32x32x16_bf16 v[146:161], v[232:235], v[228:231], v[146:161]
	v_mfma_f32_32x32x16_bf16 v[130:145], v[240:243], v[228:231], v[130:145]
	s_nop 15
	v_mul_f32_e32 v220, 0xbfb8aa3b, v192
	v_mul_f32_e32 v221, 0xbfb8aa3b, v193
	v_mul_f32_e32 v222, 0xbfb8aa3b, v190
	v_mul_f32_e32 v223, 0xbfb8aa3b, v191
	v_exp_f32_e32 v220, v220
	v_exp_f32_e32 v221, v221
	v_exp_f32_e32 v222, v222
	v_exp_f32_e32 v223, v223
	v_add_f32_e32 v220, 1.0, v220
	v_add_f32_e32 v221, 1.0, v221
	v_add_f32_e32 v222, 1.0, v222
	v_add_f32_e32 v223, 1.0, v223
	v_rcp_f32_e32 v224, v220
	v_rcp_f32_e32 v225, v221
	v_rcp_f32_e32 v226, v222
	v_rcp_f32_e32 v227, v223
	v_fma_f32 v228, -v220, v224, 1.0
	v_fma_f32 v229, -v221, v225, 1.0
	v_fma_f32 v230, -v222, v226, 1.0
	v_fma_f32 v231, -v223, v227, 1.0
	v_fmac_f32_e32 v224, v228, v224
	v_fmac_f32_e32 v225, v229, v225
	v_fmac_f32_e32 v226, v230, v226
	v_fmac_f32_e32 v227, v231, v227
	v_div_fixup_f32 v224, v224, v220, 1.0
	v_div_fixup_f32 v225, v225, v221, 1.0
	v_div_fixup_f32 v226, v226, v222, 1.0
	v_div_fixup_f32 v227, v227, v223, 1.0
	v_cvt_pk_bf16_f32 v193, v224, v225
	v_cvt_pk_bf16_f32 v192, v226, v227
	v_mul_f32_e32 v220, 0xbfb8aa3b, v188
	v_mul_f32_e32 v221, 0xbfb8aa3b, v189
	v_mul_f32_e32 v222, 0xbfb8aa3b, v186
	v_mul_f32_e32 v223, 0xbfb8aa3b, v187
	v_exp_f32_e32 v220, v220
	v_exp_f32_e32 v221, v221
	v_exp_f32_e32 v222, v222
	v_exp_f32_e32 v223, v223
	v_add_f32_e32 v220, 1.0, v220
	v_add_f32_e32 v221, 1.0, v221
	v_add_f32_e32 v222, 1.0, v222
	v_add_f32_e32 v223, 1.0, v223
	v_rcp_f32_e32 v224, v220
	v_rcp_f32_e32 v225, v221
	v_rcp_f32_e32 v226, v222
	v_rcp_f32_e32 v227, v223
	v_fma_f32 v228, -v220, v224, 1.0
	v_fma_f32 v229, -v221, v225, 1.0
	v_fma_f32 v230, -v222, v226, 1.0
	v_fma_f32 v231, -v223, v227, 1.0
	v_fmac_f32_e32 v224, v228, v224
	v_fmac_f32_e32 v225, v229, v225
	v_fmac_f32_e32 v226, v230, v226
	v_fmac_f32_e32 v227, v231, v227
	v_div_fixup_f32 v224, v224, v220, 1.0
	v_div_fixup_f32 v225, v225, v221, 1.0
	v_div_fixup_f32 v226, v226, v222, 1.0
	v_div_fixup_f32 v227, v227, v223, 1.0
	v_cvt_pk_bf16_f32 v191, v224, v225
	v_cvt_pk_bf16_f32 v190, v226, v227
	v_mul_f32_e32 v220, 0xbfb8aa3b, v184
	v_mul_f32_e32 v221, 0xbfb8aa3b, v185
	v_mul_f32_e32 v222, 0xbfb8aa3b, v182
	v_mul_f32_e32 v223, 0xbfb8aa3b, v183
	v_exp_f32_e32 v220, v220
	v_exp_f32_e32 v221, v221
	v_exp_f32_e32 v222, v222
	v_exp_f32_e32 v223, v223
	v_add_f32_e32 v220, 1.0, v220
	v_add_f32_e32 v221, 1.0, v221
	v_add_f32_e32 v222, 1.0, v222
	v_add_f32_e32 v223, 1.0, v223
	v_rcp_f32_e32 v224, v220
	v_rcp_f32_e32 v225, v221
	v_rcp_f32_e32 v226, v222
	v_rcp_f32_e32 v227, v223
	v_fma_f32 v228, -v220, v224, 1.0
	v_fma_f32 v229, -v221, v225, 1.0
	v_fma_f32 v230, -v222, v226, 1.0
	v_fma_f32 v231, -v223, v227, 1.0
	v_fmac_f32_e32 v224, v228, v224
	v_fmac_f32_e32 v225, v229, v225
	v_fmac_f32_e32 v226, v230, v226
	v_fmac_f32_e32 v227, v231, v227
	v_div_fixup_f32 v224, v224, v220, 1.0
	v_div_fixup_f32 v225, v225, v221, 1.0
	v_div_fixup_f32 v226, v226, v222, 1.0
	v_div_fixup_f32 v227, v227, v223, 1.0
	v_cvt_pk_bf16_f32 v189, v224, v225
	v_cvt_pk_bf16_f32 v188, v226, v227
	v_mul_f32_e32 v220, 0xbfb8aa3b, v180
	v_mul_f32_e32 v221, 0xbfb8aa3b, v181
	v_mul_f32_e32 v222, 0xbfb8aa3b, v178
	v_mul_f32_e32 v223, 0xbfb8aa3b, v179
	v_exp_f32_e32 v220, v220
	v_exp_f32_e32 v221, v221
	v_exp_f32_e32 v222, v222
	v_exp_f32_e32 v223, v223
	v_add_f32_e32 v220, 1.0, v220
	v_add_f32_e32 v221, 1.0, v221
	v_add_f32_e32 v222, 1.0, v222
	v_add_f32_e32 v223, 1.0, v223
	v_rcp_f32_e32 v224, v220
	v_rcp_f32_e32 v225, v221
	v_rcp_f32_e32 v226, v222
	v_rcp_f32_e32 v227, v223
	v_fma_f32 v228, -v220, v224, 1.0
	v_fma_f32 v229, -v221, v225, 1.0
	v_fma_f32 v230, -v222, v226, 1.0
	v_fma_f32 v231, -v223, v227, 1.0
	v_fmac_f32_e32 v224, v228, v224
	v_fmac_f32_e32 v225, v229, v225
	v_fmac_f32_e32 v226, v230, v226
	v_fmac_f32_e32 v227, v231, v227
	v_div_fixup_f32 v224, v224, v220, 1.0
	v_div_fixup_f32 v225, v225, v221, 1.0
	v_div_fixup_f32 v226, v226, v222, 1.0
	v_div_fixup_f32 v227, v227, v223, 1.0
	v_cvt_pk_bf16_f32 v187, v224, v225
	v_cvt_pk_bf16_f32 v186, v226, v227
	v_mul_f32_e32 v220, 0xbfb8aa3b, v176
	v_mul_f32_e32 v221, 0xbfb8aa3b, v177
	v_mul_f32_e32 v222, 0xbfb8aa3b, v174
	v_mul_f32_e32 v223, 0xbfb8aa3b, v175
	v_exp_f32_e32 v220, v220
	v_exp_f32_e32 v221, v221
	v_exp_f32_e32 v222, v222
	v_exp_f32_e32 v223, v223
	v_add_f32_e32 v220, 1.0, v220
	v_add_f32_e32 v221, 1.0, v221
	v_add_f32_e32 v222, 1.0, v222
	v_add_f32_e32 v223, 1.0, v223
	v_rcp_f32_e32 v224, v220
	v_rcp_f32_e32 v225, v221
	v_rcp_f32_e32 v226, v222
	v_rcp_f32_e32 v227, v223
	v_fma_f32 v228, -v220, v224, 1.0
	v_fma_f32 v229, -v221, v225, 1.0
	v_fma_f32 v230, -v222, v226, 1.0
	v_fma_f32 v231, -v223, v227, 1.0
	v_fmac_f32_e32 v224, v228, v224
	v_fmac_f32_e32 v225, v229, v225
	v_fmac_f32_e32 v226, v230, v226
	v_fmac_f32_e32 v227, v231, v227
	v_div_fixup_f32 v224, v224, v220, 1.0
	v_div_fixup_f32 v225, v225, v221, 1.0
	v_div_fixup_f32 v226, v226, v222, 1.0
	v_div_fixup_f32 v227, v227, v223, 1.0
	v_cvt_pk_bf16_f32 v185, v224, v225
	v_cvt_pk_bf16_f32 v184, v226, v227
	v_mul_f32_e32 v220, 0xbfb8aa3b, v172
	v_mul_f32_e32 v221, 0xbfb8aa3b, v173
	v_mul_f32_e32 v222, 0xbfb8aa3b, v170
	v_mul_f32_e32 v223, 0xbfb8aa3b, v171
	v_exp_f32_e32 v220, v220
	v_exp_f32_e32 v221, v221
	v_exp_f32_e32 v222, v222
	v_exp_f32_e32 v223, v223
	v_add_f32_e32 v220, 1.0, v220
	v_add_f32_e32 v221, 1.0, v221
	v_add_f32_e32 v222, 1.0, v222
	v_add_f32_e32 v223, 1.0, v223
	v_rcp_f32_e32 v224, v220
	v_rcp_f32_e32 v225, v221
	v_rcp_f32_e32 v226, v222
	v_rcp_f32_e32 v227, v223
	v_fma_f32 v228, -v220, v224, 1.0
	v_fma_f32 v229, -v221, v225, 1.0
	v_fma_f32 v230, -v222, v226, 1.0
	v_fma_f32 v231, -v223, v227, 1.0
	v_fmac_f32_e32 v224, v228, v224
	v_fmac_f32_e32 v225, v229, v225
	v_fmac_f32_e32 v226, v230, v226
	v_fmac_f32_e32 v227, v231, v227
	v_div_fixup_f32 v224, v224, v220, 1.0
	v_div_fixup_f32 v225, v225, v221, 1.0
	v_div_fixup_f32 v226, v226, v222, 1.0
	v_div_fixup_f32 v227, v227, v223, 1.0
	v_cvt_pk_bf16_f32 v183, v224, v225
	v_cvt_pk_bf16_f32 v182, v226, v227
	v_mul_f32_e32 v220, 0xbfb8aa3b, v168
	v_mul_f32_e32 v221, 0xbfb8aa3b, v169
	v_mul_f32_e32 v222, 0xbfb8aa3b, v166
	v_mul_f32_e32 v223, 0xbfb8aa3b, v167
	v_exp_f32_e32 v220, v220
	v_exp_f32_e32 v221, v221
	v_exp_f32_e32 v222, v222
	v_exp_f32_e32 v223, v223
	v_add_f32_e32 v220, 1.0, v220
	v_add_f32_e32 v221, 1.0, v221
	v_add_f32_e32 v222, 1.0, v222
	v_add_f32_e32 v223, 1.0, v223
	v_rcp_f32_e32 v224, v220
	v_rcp_f32_e32 v225, v221
	v_rcp_f32_e32 v226, v222
	v_rcp_f32_e32 v227, v223
	v_fma_f32 v228, -v220, v224, 1.0
	v_fma_f32 v229, -v221, v225, 1.0
	v_fma_f32 v230, -v222, v226, 1.0
	v_fma_f32 v231, -v223, v227, 1.0
	v_fmac_f32_e32 v224, v228, v224
	v_fmac_f32_e32 v225, v229, v225
	v_fmac_f32_e32 v226, v230, v226
	v_fmac_f32_e32 v227, v231, v227
	v_div_fixup_f32 v224, v224, v220, 1.0
	v_div_fixup_f32 v225, v225, v221, 1.0
	v_div_fixup_f32 v226, v226, v222, 1.0
	v_div_fixup_f32 v227, v227, v223, 1.0
	v_cvt_pk_bf16_f32 v181, v224, v225
	v_cvt_pk_bf16_f32 v180, v226, v227
	v_mul_f32_e32 v220, 0xbfb8aa3b, v164
	v_mul_f32_e32 v221, 0xbfb8aa3b, v165
	v_mul_f32_e32 v222, 0xbfb8aa3b, v162
	v_mul_f32_e32 v223, 0xbfb8aa3b, v163
	v_exp_f32_e32 v220, v220
	v_exp_f32_e32 v221, v221
	v_exp_f32_e32 v222, v222
	v_exp_f32_e32 v223, v223
	v_add_f32_e32 v220, 1.0, v220
	v_add_f32_e32 v221, 1.0, v221
	v_add_f32_e32 v222, 1.0, v222
	v_add_f32_e32 v223, 1.0, v223
	v_rcp_f32_e32 v224, v220
	v_rcp_f32_e32 v225, v221
	v_rcp_f32_e32 v226, v222
	v_rcp_f32_e32 v227, v223
	v_fma_f32 v228, -v220, v224, 1.0
	v_fma_f32 v229, -v221, v225, 1.0
	v_fma_f32 v230, -v222, v226, 1.0
	v_fma_f32 v231, -v223, v227, 1.0
	v_fmac_f32_e32 v224, v228, v224
	v_fmac_f32_e32 v225, v229, v225
	v_fmac_f32_e32 v226, v230, v226
	v_fmac_f32_e32 v227, v231, v227
	v_div_fixup_f32 v224, v224, v220, 1.0
	v_div_fixup_f32 v225, v225, v221, 1.0
	v_div_fixup_f32 v226, v226, v222, 1.0
	v_div_fixup_f32 v227, v227, v223, 1.0
	v_cvt_pk_bf16_f32 v179, v224, v225
	v_cvt_pk_bf16_f32 v178, v226, v227
	v_mul_f32_e32 v220, 0xbfb8aa3b, v160
	v_mul_f32_e32 v221, 0xbfb8aa3b, v161
	v_mul_f32_e32 v222, 0xbfb8aa3b, v158
	v_mul_f32_e32 v223, 0xbfb8aa3b, v159
	v_exp_f32_e32 v220, v220
	v_exp_f32_e32 v221, v221
	v_exp_f32_e32 v222, v222
	v_exp_f32_e32 v223, v223
	v_add_f32_e32 v220, 1.0, v220
	v_add_f32_e32 v221, 1.0, v221
	v_add_f32_e32 v222, 1.0, v222
	v_add_f32_e32 v223, 1.0, v223
	v_rcp_f32_e32 v224, v220
	v_rcp_f32_e32 v225, v221
	v_rcp_f32_e32 v226, v222
	v_rcp_f32_e32 v227, v223
	v_fma_f32 v228, -v220, v224, 1.0
	v_fma_f32 v229, -v221, v225, 1.0
	v_fma_f32 v230, -v222, v226, 1.0
	v_fma_f32 v231, -v223, v227, 1.0
	v_fmac_f32_e32 v224, v228, v224
	v_fmac_f32_e32 v225, v229, v225
	v_fmac_f32_e32 v226, v230, v226
	v_fmac_f32_e32 v227, v231, v227
	v_div_fixup_f32 v224, v224, v220, 1.0
	v_div_fixup_f32 v225, v225, v221, 1.0
	v_div_fixup_f32 v226, v226, v222, 1.0
	v_div_fixup_f32 v227, v227, v223, 1.0
	v_cvt_pk_bf16_f32 v177, v224, v225
	v_cvt_pk_bf16_f32 v176, v226, v227
	v_mul_f32_e32 v220, 0xbfb8aa3b, v156
	v_mul_f32_e32 v221, 0xbfb8aa3b, v157
	v_mul_f32_e32 v222, 0xbfb8aa3b, v154
	v_mul_f32_e32 v223, 0xbfb8aa3b, v155
	v_exp_f32_e32 v220, v220
	v_exp_f32_e32 v221, v221
	v_exp_f32_e32 v222, v222
	v_exp_f32_e32 v223, v223
	v_add_f32_e32 v220, 1.0, v220
	v_add_f32_e32 v221, 1.0, v221
	v_add_f32_e32 v222, 1.0, v222
	v_add_f32_e32 v223, 1.0, v223
	v_rcp_f32_e32 v224, v220
	v_rcp_f32_e32 v225, v221
	v_rcp_f32_e32 v226, v222
	v_rcp_f32_e32 v227, v223
	v_fma_f32 v228, -v220, v224, 1.0
	v_fma_f32 v229, -v221, v225, 1.0
	v_fma_f32 v230, -v222, v226, 1.0
	v_fma_f32 v231, -v223, v227, 1.0
	v_fmac_f32_e32 v224, v228, v224
	v_fmac_f32_e32 v225, v229, v225
	v_fmac_f32_e32 v226, v230, v226
	v_fmac_f32_e32 v227, v231, v227
	v_div_fixup_f32 v224, v224, v220, 1.0
	v_div_fixup_f32 v225, v225, v221, 1.0
	v_div_fixup_f32 v226, v226, v222, 1.0
	v_div_fixup_f32 v227, v227, v223, 1.0
	v_cvt_pk_bf16_f32 v175, v224, v225
	v_cvt_pk_bf16_f32 v174, v226, v227
	v_mul_f32_e32 v220, 0xbfb8aa3b, v152
	v_mul_f32_e32 v221, 0xbfb8aa3b, v153
	v_mul_f32_e32 v222, 0xbfb8aa3b, v150
	v_mul_f32_e32 v223, 0xbfb8aa3b, v151
	v_exp_f32_e32 v220, v220
	v_exp_f32_e32 v221, v221
	v_exp_f32_e32 v222, v222
	v_exp_f32_e32 v223, v223
	v_add_f32_e32 v220, 1.0, v220
	v_add_f32_e32 v221, 1.0, v221
	v_add_f32_e32 v222, 1.0, v222
	v_add_f32_e32 v223, 1.0, v223
	v_rcp_f32_e32 v224, v220
	v_rcp_f32_e32 v225, v221
	v_rcp_f32_e32 v226, v222
	v_rcp_f32_e32 v227, v223
	v_fma_f32 v228, -v220, v224, 1.0
	v_fma_f32 v229, -v221, v225, 1.0
	v_fma_f32 v230, -v222, v226, 1.0
	v_fma_f32 v231, -v223, v227, 1.0
	v_fmac_f32_e32 v224, v228, v224
	v_fmac_f32_e32 v225, v229, v225
	v_fmac_f32_e32 v226, v230, v226
	v_fmac_f32_e32 v227, v231, v227
	v_div_fixup_f32 v224, v224, v220, 1.0
	v_div_fixup_f32 v225, v225, v221, 1.0
	v_div_fixup_f32 v226, v226, v222, 1.0
	v_div_fixup_f32 v227, v227, v223, 1.0
	v_cvt_pk_bf16_f32 v173, v224, v225
	v_cvt_pk_bf16_f32 v172, v226, v227
	v_mul_f32_e32 v220, 0xbfb8aa3b, v148
	v_mul_f32_e32 v221, 0xbfb8aa3b, v149
	v_mul_f32_e32 v222, 0xbfb8aa3b, v146
	v_mul_f32_e32 v223, 0xbfb8aa3b, v147
	v_exp_f32_e32 v220, v220
	v_exp_f32_e32 v221, v221
	v_exp_f32_e32 v222, v222
	v_exp_f32_e32 v223, v223
	v_add_f32_e32 v220, 1.0, v220
	v_add_f32_e32 v221, 1.0, v221
	v_add_f32_e32 v222, 1.0, v222
	v_add_f32_e32 v223, 1.0, v223
	v_rcp_f32_e32 v224, v220
	v_rcp_f32_e32 v225, v221
	v_rcp_f32_e32 v226, v222
	v_rcp_f32_e32 v227, v223
	v_fma_f32 v228, -v220, v224, 1.0
	v_fma_f32 v229, -v221, v225, 1.0
	v_fma_f32 v230, -v222, v226, 1.0
	v_fma_f32 v231, -v223, v227, 1.0
	v_fmac_f32_e32 v224, v228, v224
	v_fmac_f32_e32 v225, v229, v225
	v_fmac_f32_e32 v226, v230, v226
	v_fmac_f32_e32 v227, v231, v227
	v_div_fixup_f32 v224, v224, v220, 1.0
	v_div_fixup_f32 v225, v225, v221, 1.0
	v_div_fixup_f32 v226, v226, v222, 1.0
	v_div_fixup_f32 v227, v227, v223, 1.0
	v_cvt_pk_bf16_f32 v171, v224, v225
	v_cvt_pk_bf16_f32 v170, v226, v227
	v_mul_f32_e32 v220, 0xbfb8aa3b, v144
	v_mul_f32_e32 v221, 0xbfb8aa3b, v145
	v_mul_f32_e32 v222, 0xbfb8aa3b, v142
	v_mul_f32_e32 v223, 0xbfb8aa3b, v143
	v_exp_f32_e32 v220, v220
	v_exp_f32_e32 v221, v221
	v_exp_f32_e32 v222, v222
	v_exp_f32_e32 v223, v223
	v_add_f32_e32 v220, 1.0, v220
	v_add_f32_e32 v221, 1.0, v221
	v_add_f32_e32 v222, 1.0, v222
	v_add_f32_e32 v223, 1.0, v223
	v_rcp_f32_e32 v224, v220
	v_rcp_f32_e32 v225, v221
	v_rcp_f32_e32 v226, v222
	v_rcp_f32_e32 v227, v223
	v_fma_f32 v228, -v220, v224, 1.0
	v_fma_f32 v229, -v221, v225, 1.0
	v_fma_f32 v230, -v222, v226, 1.0
	v_fma_f32 v231, -v223, v227, 1.0
	v_fmac_f32_e32 v224, v228, v224
	v_fmac_f32_e32 v225, v229, v225
	v_fmac_f32_e32 v226, v230, v226
	v_fmac_f32_e32 v227, v231, v227
	v_div_fixup_f32 v224, v224, v220, 1.0
	v_div_fixup_f32 v225, v225, v221, 1.0
	v_div_fixup_f32 v226, v226, v222, 1.0
	v_div_fixup_f32 v227, v227, v223, 1.0
	v_cvt_pk_bf16_f32 v169, v224, v225
	v_cvt_pk_bf16_f32 v168, v226, v227
	v_mul_f32_e32 v220, 0xbfb8aa3b, v140
	v_mul_f32_e32 v221, 0xbfb8aa3b, v141
	v_mul_f32_e32 v222, 0xbfb8aa3b, v138
	v_mul_f32_e32 v223, 0xbfb8aa3b, v139
	v_exp_f32_e32 v220, v220
	v_exp_f32_e32 v221, v221
	v_exp_f32_e32 v222, v222
	v_exp_f32_e32 v223, v223
	v_add_f32_e32 v220, 1.0, v220
	v_add_f32_e32 v221, 1.0, v221
	v_add_f32_e32 v222, 1.0, v222
	v_add_f32_e32 v223, 1.0, v223
	v_rcp_f32_e32 v224, v220
	v_rcp_f32_e32 v225, v221
	v_rcp_f32_e32 v226, v222
	v_rcp_f32_e32 v227, v223
	v_fma_f32 v228, -v220, v224, 1.0
	v_fma_f32 v229, -v221, v225, 1.0
	v_fma_f32 v230, -v222, v226, 1.0
	v_fma_f32 v231, -v223, v227, 1.0
	v_fmac_f32_e32 v224, v228, v224
	v_fmac_f32_e32 v225, v229, v225
	v_fmac_f32_e32 v226, v230, v226
	v_fmac_f32_e32 v227, v231, v227
	v_div_fixup_f32 v224, v224, v220, 1.0
	v_div_fixup_f32 v225, v225, v221, 1.0
	v_div_fixup_f32 v226, v226, v222, 1.0
	v_div_fixup_f32 v227, v227, v223, 1.0
	v_cvt_pk_bf16_f32 v167, v224, v225
	v_cvt_pk_bf16_f32 v166, v226, v227
	v_mul_f32_e32 v220, 0xbfb8aa3b, v136
	v_mul_f32_e32 v221, 0xbfb8aa3b, v137
	v_mul_f32_e32 v222, 0xbfb8aa3b, v134
	v_mul_f32_e32 v223, 0xbfb8aa3b, v135
	v_exp_f32_e32 v220, v220
	v_exp_f32_e32 v221, v221
	v_exp_f32_e32 v222, v222
	v_exp_f32_e32 v223, v223
	v_add_f32_e32 v220, 1.0, v220
	v_add_f32_e32 v221, 1.0, v221
	v_add_f32_e32 v222, 1.0, v222
	v_add_f32_e32 v223, 1.0, v223
	v_rcp_f32_e32 v224, v220
	v_rcp_f32_e32 v225, v221
	v_rcp_f32_e32 v226, v222
	v_rcp_f32_e32 v227, v223
	v_fma_f32 v228, -v220, v224, 1.0
	v_fma_f32 v229, -v221, v225, 1.0
	v_fma_f32 v230, -v222, v226, 1.0
	v_fma_f32 v231, -v223, v227, 1.0
	v_fmac_f32_e32 v224, v228, v224
	v_fmac_f32_e32 v225, v229, v225
	v_fmac_f32_e32 v226, v230, v226
	v_fmac_f32_e32 v227, v231, v227
	v_div_fixup_f32 v224, v224, v220, 1.0
	v_div_fixup_f32 v225, v225, v221, 1.0
	v_div_fixup_f32 v226, v226, v222, 1.0
	v_div_fixup_f32 v227, v227, v223, 1.0
	v_cvt_pk_bf16_f32 v165, v224, v225
	v_cvt_pk_bf16_f32 v164, v226, v227
	v_mul_f32_e32 v220, 0xbfb8aa3b, v132
	v_mul_f32_e32 v221, 0xbfb8aa3b, v133
	v_mul_f32_e32 v222, 0xbfb8aa3b, v130
	v_mul_f32_e32 v223, 0xbfb8aa3b, v131
	v_exp_f32_e32 v220, v220
	v_exp_f32_e32 v221, v221
	v_exp_f32_e32 v222, v222
	v_exp_f32_e32 v223, v223
	v_add_f32_e32 v220, 1.0, v220
	v_add_f32_e32 v221, 1.0, v221
	v_add_f32_e32 v222, 1.0, v222
	v_add_f32_e32 v223, 1.0, v223
	v_rcp_f32_e32 v224, v220
	v_rcp_f32_e32 v225, v221
	v_rcp_f32_e32 v226, v222
	v_rcp_f32_e32 v227, v223
	v_fma_f32 v228, -v220, v224, 1.0
	v_fma_f32 v229, -v221, v225, 1.0
	v_fma_f32 v230, -v222, v226, 1.0
	v_fma_f32 v231, -v223, v227, 1.0
	v_fmac_f32_e32 v224, v228, v224
	v_fmac_f32_e32 v225, v229, v225
	v_fmac_f32_e32 v226, v230, v226
	v_fmac_f32_e32 v227, v231, v227
	v_div_fixup_f32 v224, v224, v220, 1.0
	v_div_fixup_f32 v225, v225, v221, 1.0
	v_div_fixup_f32 v226, v226, v222, 1.0
	v_div_fixup_f32 v227, v227, v223, 1.0
	v_cvt_pk_bf16_f32 v163, v224, v225
	v_cvt_pk_bf16_f32 v162, v226, v227
	v_mul_f32_e32 v220, 0xbfb8aa3b, v128
	v_mul_f32_e32 v221, 0xbfb8aa3b, v129
	v_mul_f32_e32 v222, 0xbfb8aa3b, v126
	v_mul_f32_e32 v223, 0xbfb8aa3b, v127
	v_exp_f32_e32 v220, v220
	v_exp_f32_e32 v221, v221
	v_exp_f32_e32 v222, v222
	v_exp_f32_e32 v223, v223
	v_add_f32_e32 v220, 1.0, v220
	v_add_f32_e32 v221, 1.0, v221
	v_add_f32_e32 v222, 1.0, v222
	v_add_f32_e32 v223, 1.0, v223
	v_rcp_f32_e32 v224, v220
	v_rcp_f32_e32 v225, v221
	v_rcp_f32_e32 v226, v222
	v_rcp_f32_e32 v227, v223
	v_fma_f32 v228, -v220, v224, 1.0
	v_fma_f32 v229, -v221, v225, 1.0
	v_fma_f32 v230, -v222, v226, 1.0
	v_fma_f32 v231, -v223, v227, 1.0
	v_fmac_f32_e32 v224, v228, v224
	v_fmac_f32_e32 v225, v229, v225
	v_fmac_f32_e32 v226, v230, v226
	v_fmac_f32_e32 v227, v231, v227
	v_div_fixup_f32 v224, v224, v220, 1.0
	v_div_fixup_f32 v225, v225, v221, 1.0
	v_div_fixup_f32 v226, v226, v222, 1.0
	v_div_fixup_f32 v227, v227, v223, 1.0
	v_cvt_pk_bf16_f32 v161, v224, v225
	v_cvt_pk_bf16_f32 v160, v226, v227
	v_mul_f32_e32 v220, 0xbfb8aa3b, v124
	v_mul_f32_e32 v221, 0xbfb8aa3b, v125
	v_mul_f32_e32 v222, 0xbfb8aa3b, v122
	v_mul_f32_e32 v223, 0xbfb8aa3b, v123
	v_exp_f32_e32 v220, v220
	v_exp_f32_e32 v221, v221
	v_exp_f32_e32 v222, v222
	v_exp_f32_e32 v223, v223
	v_add_f32_e32 v220, 1.0, v220
	v_add_f32_e32 v221, 1.0, v221
	v_add_f32_e32 v222, 1.0, v222
	v_add_f32_e32 v223, 1.0, v223
	v_rcp_f32_e32 v224, v220
	v_rcp_f32_e32 v225, v221
	v_rcp_f32_e32 v226, v222
	v_rcp_f32_e32 v227, v223
	v_fma_f32 v228, -v220, v224, 1.0
	v_fma_f32 v229, -v221, v225, 1.0
	v_fma_f32 v230, -v222, v226, 1.0
	v_fma_f32 v231, -v223, v227, 1.0
	v_fmac_f32_e32 v224, v228, v224
	v_fmac_f32_e32 v225, v229, v225
	v_fmac_f32_e32 v226, v230, v226
	v_fmac_f32_e32 v227, v231, v227
	v_div_fixup_f32 v224, v224, v220, 1.0
	v_div_fixup_f32 v225, v225, v221, 1.0
	v_div_fixup_f32 v226, v226, v222, 1.0
	v_div_fixup_f32 v227, v227, v223, 1.0
	v_cvt_pk_bf16_f32 v159, v224, v225
	v_cvt_pk_bf16_f32 v158, v226, v227
	v_mul_f32_e32 v220, 0xbfb8aa3b, v120
	v_mul_f32_e32 v221, 0xbfb8aa3b, v121
	v_mul_f32_e32 v222, 0xbfb8aa3b, v118
	v_mul_f32_e32 v223, 0xbfb8aa3b, v119
	v_exp_f32_e32 v220, v220
	v_exp_f32_e32 v221, v221
	v_exp_f32_e32 v222, v222
	v_exp_f32_e32 v223, v223
	v_add_f32_e32 v220, 1.0, v220
	v_add_f32_e32 v221, 1.0, v221
	v_add_f32_e32 v222, 1.0, v222
	v_add_f32_e32 v223, 1.0, v223
	v_rcp_f32_e32 v224, v220
	v_rcp_f32_e32 v225, v221
	v_rcp_f32_e32 v226, v222
	v_rcp_f32_e32 v227, v223
	v_fma_f32 v228, -v220, v224, 1.0
	v_fma_f32 v229, -v221, v225, 1.0
	v_fma_f32 v230, -v222, v226, 1.0
	v_fma_f32 v231, -v223, v227, 1.0
	v_fmac_f32_e32 v224, v228, v224
	v_fmac_f32_e32 v225, v229, v225
	v_fmac_f32_e32 v226, v230, v226
	v_fmac_f32_e32 v227, v231, v227
	v_div_fixup_f32 v224, v224, v220, 1.0
	v_div_fixup_f32 v225, v225, v221, 1.0
	v_div_fixup_f32 v226, v226, v222, 1.0
	v_div_fixup_f32 v227, v227, v223, 1.0
	v_cvt_pk_bf16_f32 v157, v224, v225
	v_cvt_pk_bf16_f32 v156, v226, v227
	v_mul_f32_e32 v220, 0xbfb8aa3b, v116
	v_mul_f32_e32 v221, 0xbfb8aa3b, v117
	v_mul_f32_e32 v222, 0xbfb8aa3b, v114
	v_mul_f32_e32 v223, 0xbfb8aa3b, v115
	v_exp_f32_e32 v220, v220
	v_exp_f32_e32 v221, v221
	v_exp_f32_e32 v222, v222
	v_exp_f32_e32 v223, v223
	v_add_f32_e32 v220, 1.0, v220
	v_add_f32_e32 v221, 1.0, v221
	v_add_f32_e32 v222, 1.0, v222
	v_add_f32_e32 v223, 1.0, v223
	v_rcp_f32_e32 v224, v220
	v_rcp_f32_e32 v225, v221
	v_rcp_f32_e32 v226, v222
	v_rcp_f32_e32 v227, v223
	v_fma_f32 v228, -v220, v224, 1.0
	v_fma_f32 v229, -v221, v225, 1.0
	v_fma_f32 v230, -v222, v226, 1.0
	v_fma_f32 v231, -v223, v227, 1.0
	v_fmac_f32_e32 v224, v228, v224
	v_fmac_f32_e32 v225, v229, v225
	v_fmac_f32_e32 v226, v230, v226
	v_fmac_f32_e32 v227, v231, v227
	v_div_fixup_f32 v224, v224, v220, 1.0
	v_div_fixup_f32 v225, v225, v221, 1.0
	v_div_fixup_f32 v226, v226, v222, 1.0
	v_div_fixup_f32 v227, v227, v223, 1.0
	v_cvt_pk_bf16_f32 v155, v224, v225
	v_cvt_pk_bf16_f32 v154, v226, v227
	v_mul_f32_e32 v220, 0xbfb8aa3b, v112
	v_mul_f32_e32 v221, 0xbfb8aa3b, v113
	v_mul_f32_e32 v222, 0xbfb8aa3b, v110
	v_mul_f32_e32 v223, 0xbfb8aa3b, v111
	v_exp_f32_e32 v220, v220
	v_exp_f32_e32 v221, v221
	v_exp_f32_e32 v222, v222
	v_exp_f32_e32 v223, v223
	v_add_f32_e32 v220, 1.0, v220
	v_add_f32_e32 v221, 1.0, v221
	v_add_f32_e32 v222, 1.0, v222
	v_add_f32_e32 v223, 1.0, v223
	v_rcp_f32_e32 v224, v220
	v_rcp_f32_e32 v225, v221
	v_rcp_f32_e32 v226, v222
	v_rcp_f32_e32 v227, v223
	v_fma_f32 v228, -v220, v224, 1.0
	v_fma_f32 v229, -v221, v225, 1.0
	v_fma_f32 v230, -v222, v226, 1.0
	v_fma_f32 v231, -v223, v227, 1.0
	v_fmac_f32_e32 v224, v228, v224
	v_fmac_f32_e32 v225, v229, v225
	v_fmac_f32_e32 v226, v230, v226
	v_fmac_f32_e32 v227, v231, v227
	v_div_fixup_f32 v224, v224, v220, 1.0
	v_div_fixup_f32 v225, v225, v221, 1.0
	v_div_fixup_f32 v226, v226, v222, 1.0
	v_div_fixup_f32 v227, v227, v223, 1.0
	v_cvt_pk_bf16_f32 v153, v224, v225
	v_cvt_pk_bf16_f32 v152, v226, v227
	v_mul_f32_e32 v220, 0xbfb8aa3b, v108
	v_mul_f32_e32 v221, 0xbfb8aa3b, v109
	v_mul_f32_e32 v222, 0xbfb8aa3b, v106
	v_mul_f32_e32 v223, 0xbfb8aa3b, v107
	v_exp_f32_e32 v220, v220
	v_exp_f32_e32 v221, v221
	v_exp_f32_e32 v222, v222
	v_exp_f32_e32 v223, v223
	v_add_f32_e32 v220, 1.0, v220
	v_add_f32_e32 v221, 1.0, v221
	v_add_f32_e32 v222, 1.0, v222
	v_add_f32_e32 v223, 1.0, v223
	v_rcp_f32_e32 v224, v220
	v_rcp_f32_e32 v225, v221
	v_rcp_f32_e32 v226, v222
	v_rcp_f32_e32 v227, v223
	v_fma_f32 v228, -v220, v224, 1.0
	v_fma_f32 v229, -v221, v225, 1.0
	v_fma_f32 v230, -v222, v226, 1.0
	v_fma_f32 v231, -v223, v227, 1.0
	v_fmac_f32_e32 v224, v228, v224
	v_fmac_f32_e32 v225, v229, v225
	v_fmac_f32_e32 v226, v230, v226
	v_fmac_f32_e32 v227, v231, v227
	v_div_fixup_f32 v224, v224, v220, 1.0
	v_div_fixup_f32 v225, v225, v221, 1.0
	v_div_fixup_f32 v226, v226, v222, 1.0
	v_div_fixup_f32 v227, v227, v223, 1.0
	v_cvt_pk_bf16_f32 v151, v224, v225
	v_cvt_pk_bf16_f32 v150, v226, v227
	v_mul_f32_e32 v220, 0xbfb8aa3b, v104
	v_mul_f32_e32 v221, 0xbfb8aa3b, v105
	v_mul_f32_e32 v222, 0xbfb8aa3b, v102
	v_mul_f32_e32 v223, 0xbfb8aa3b, v103
	v_exp_f32_e32 v220, v220
	v_exp_f32_e32 v221, v221
	v_exp_f32_e32 v222, v222
	v_exp_f32_e32 v223, v223
	v_add_f32_e32 v220, 1.0, v220
	v_add_f32_e32 v221, 1.0, v221
	v_add_f32_e32 v222, 1.0, v222
	v_add_f32_e32 v223, 1.0, v223
	v_rcp_f32_e32 v224, v220
	v_rcp_f32_e32 v225, v221
	v_rcp_f32_e32 v226, v222
	v_rcp_f32_e32 v227, v223
	v_fma_f32 v228, -v220, v224, 1.0
	v_fma_f32 v229, -v221, v225, 1.0
	v_fma_f32 v230, -v222, v226, 1.0
	v_fma_f32 v231, -v223, v227, 1.0
	v_fmac_f32_e32 v224, v228, v224
	v_fmac_f32_e32 v225, v229, v225
	v_fmac_f32_e32 v226, v230, v226
	v_fmac_f32_e32 v227, v231, v227
	v_div_fixup_f32 v224, v224, v220, 1.0
	v_div_fixup_f32 v225, v225, v221, 1.0
	v_div_fixup_f32 v226, v226, v222, 1.0
	v_div_fixup_f32 v227, v227, v223, 1.0
	v_cvt_pk_bf16_f32 v149, v224, v225
	v_cvt_pk_bf16_f32 v148, v226, v227
	v_mul_f32_e32 v220, 0xbfb8aa3b, v100
	v_mul_f32_e32 v221, 0xbfb8aa3b, v101
	v_mul_f32_e32 v222, 0xbfb8aa3b, v98
	v_mul_f32_e32 v223, 0xbfb8aa3b, v99
	v_exp_f32_e32 v220, v220
	v_exp_f32_e32 v221, v221
	v_exp_f32_e32 v222, v222
	v_exp_f32_e32 v223, v223
	v_add_f32_e32 v220, 1.0, v220
	v_add_f32_e32 v221, 1.0, v221
	v_add_f32_e32 v222, 1.0, v222
	v_add_f32_e32 v223, 1.0, v223
	v_rcp_f32_e32 v224, v220
	v_rcp_f32_e32 v225, v221
	v_rcp_f32_e32 v226, v222
	v_rcp_f32_e32 v227, v223
	v_fma_f32 v228, -v220, v224, 1.0
	v_fma_f32 v229, -v221, v225, 1.0
	v_fma_f32 v230, -v222, v226, 1.0
	v_fma_f32 v231, -v223, v227, 1.0
	v_fmac_f32_e32 v224, v228, v224
	v_fmac_f32_e32 v225, v229, v225
	v_fmac_f32_e32 v226, v230, v226
	v_fmac_f32_e32 v227, v231, v227
	v_div_fixup_f32 v224, v224, v220, 1.0
	v_div_fixup_f32 v225, v225, v221, 1.0
	v_div_fixup_f32 v226, v226, v222, 1.0
	v_div_fixup_f32 v227, v227, v223, 1.0
	v_cvt_pk_bf16_f32 v147, v224, v225
	v_cvt_pk_bf16_f32 v146, v226, v227
	v_mul_f32_e32 v220, 0xbfb8aa3b, v96
	v_mul_f32_e32 v221, 0xbfb8aa3b, v97
	v_mul_f32_e32 v222, 0xbfb8aa3b, v94
	v_mul_f32_e32 v223, 0xbfb8aa3b, v95
	v_exp_f32_e32 v220, v220
	v_exp_f32_e32 v221, v221
	v_exp_f32_e32 v222, v222
	v_exp_f32_e32 v223, v223
	v_add_f32_e32 v220, 1.0, v220
	v_add_f32_e32 v221, 1.0, v221
	v_add_f32_e32 v222, 1.0, v222
	v_add_f32_e32 v223, 1.0, v223
	v_rcp_f32_e32 v224, v220
	v_rcp_f32_e32 v225, v221
	v_rcp_f32_e32 v226, v222
	v_rcp_f32_e32 v227, v223
	v_fma_f32 v228, -v220, v224, 1.0
	v_fma_f32 v229, -v221, v225, 1.0
	v_fma_f32 v230, -v222, v226, 1.0
	v_fma_f32 v231, -v223, v227, 1.0
	v_fmac_f32_e32 v224, v228, v224
	v_fmac_f32_e32 v225, v229, v225
	v_fmac_f32_e32 v226, v230, v226
	v_fmac_f32_e32 v227, v231, v227
	v_div_fixup_f32 v224, v224, v220, 1.0
	v_div_fixup_f32 v225, v225, v221, 1.0
	v_div_fixup_f32 v226, v226, v222, 1.0
	v_div_fixup_f32 v227, v227, v223, 1.0
	v_cvt_pk_bf16_f32 v145, v224, v225
	v_cvt_pk_bf16_f32 v144, v226, v227
	v_mul_f32_e32 v220, 0xbfb8aa3b, v92
	v_mul_f32_e32 v221, 0xbfb8aa3b, v93
	v_mul_f32_e32 v222, 0xbfb8aa3b, v90
	v_mul_f32_e32 v223, 0xbfb8aa3b, v91
	v_exp_f32_e32 v220, v220
	v_exp_f32_e32 v221, v221
	v_exp_f32_e32 v222, v222
	v_exp_f32_e32 v223, v223
	v_add_f32_e32 v220, 1.0, v220
	v_add_f32_e32 v221, 1.0, v221
	v_add_f32_e32 v222, 1.0, v222
	v_add_f32_e32 v223, 1.0, v223
	v_rcp_f32_e32 v224, v220
	v_rcp_f32_e32 v225, v221
	v_rcp_f32_e32 v226, v222
	v_rcp_f32_e32 v227, v223
	v_fma_f32 v228, -v220, v224, 1.0
	v_fma_f32 v229, -v221, v225, 1.0
	v_fma_f32 v230, -v222, v226, 1.0
	v_fma_f32 v231, -v223, v227, 1.0
	v_fmac_f32_e32 v224, v228, v224
	v_fmac_f32_e32 v225, v229, v225
	v_fmac_f32_e32 v226, v230, v226
	v_fmac_f32_e32 v227, v231, v227
	v_div_fixup_f32 v224, v224, v220, 1.0
	v_div_fixup_f32 v225, v225, v221, 1.0
	v_div_fixup_f32 v226, v226, v222, 1.0
	v_div_fixup_f32 v227, v227, v223, 1.0
	v_cvt_pk_bf16_f32 v143, v224, v225
	v_cvt_pk_bf16_f32 v142, v226, v227
	v_mul_f32_e32 v220, 0xbfb8aa3b, v88
	v_mul_f32_e32 v221, 0xbfb8aa3b, v89
	v_mul_f32_e32 v222, 0xbfb8aa3b, v86
	v_mul_f32_e32 v223, 0xbfb8aa3b, v87
	v_exp_f32_e32 v220, v220
	v_exp_f32_e32 v221, v221
	v_exp_f32_e32 v222, v222
	v_exp_f32_e32 v223, v223
	v_add_f32_e32 v220, 1.0, v220
	v_add_f32_e32 v221, 1.0, v221
	v_add_f32_e32 v222, 1.0, v222
	v_add_f32_e32 v223, 1.0, v223
	v_rcp_f32_e32 v224, v220
	v_rcp_f32_e32 v225, v221
	v_rcp_f32_e32 v226, v222
	v_rcp_f32_e32 v227, v223
	v_fma_f32 v228, -v220, v224, 1.0
	v_fma_f32 v229, -v221, v225, 1.0
	v_fma_f32 v230, -v222, v226, 1.0
	v_fma_f32 v231, -v223, v227, 1.0
	v_fmac_f32_e32 v224, v228, v224
	v_fmac_f32_e32 v225, v229, v225
	v_fmac_f32_e32 v226, v230, v226
	v_fmac_f32_e32 v227, v231, v227
	v_div_fixup_f32 v224, v224, v220, 1.0
	v_div_fixup_f32 v225, v225, v221, 1.0
	v_div_fixup_f32 v226, v226, v222, 1.0
	v_div_fixup_f32 v227, v227, v223, 1.0
	v_cvt_pk_bf16_f32 v141, v224, v225
	v_cvt_pk_bf16_f32 v140, v226, v227
	v_mul_f32_e32 v220, 0xbfb8aa3b, v84
	v_mul_f32_e32 v221, 0xbfb8aa3b, v85
	v_mul_f32_e32 v222, 0xbfb8aa3b, v82
	v_mul_f32_e32 v223, 0xbfb8aa3b, v83
	v_exp_f32_e32 v220, v220
	v_exp_f32_e32 v221, v221
	v_exp_f32_e32 v222, v222
	v_exp_f32_e32 v223, v223
	v_add_f32_e32 v220, 1.0, v220
	v_add_f32_e32 v221, 1.0, v221
	v_add_f32_e32 v222, 1.0, v222
	v_add_f32_e32 v223, 1.0, v223
	v_rcp_f32_e32 v224, v220
	v_rcp_f32_e32 v225, v221
	v_rcp_f32_e32 v226, v222
	v_rcp_f32_e32 v227, v223
	v_fma_f32 v228, -v220, v224, 1.0
	v_fma_f32 v229, -v221, v225, 1.0
	v_fma_f32 v230, -v222, v226, 1.0
	v_fma_f32 v231, -v223, v227, 1.0
	v_fmac_f32_e32 v224, v228, v224
	v_fmac_f32_e32 v225, v229, v225
	v_fmac_f32_e32 v226, v230, v226
	v_fmac_f32_e32 v227, v231, v227
	v_div_fixup_f32 v224, v224, v220, 1.0
	v_div_fixup_f32 v225, v225, v221, 1.0
	v_div_fixup_f32 v226, v226, v222, 1.0
	v_div_fixup_f32 v227, v227, v223, 1.0
	v_cvt_pk_bf16_f32 v139, v224, v225
	v_cvt_pk_bf16_f32 v138, v226, v227
	v_mul_f32_e32 v220, 0xbfb8aa3b, v80
	v_mul_f32_e32 v221, 0xbfb8aa3b, v81
	v_mul_f32_e32 v222, 0xbfb8aa3b, v78
	v_mul_f32_e32 v223, 0xbfb8aa3b, v79
	v_exp_f32_e32 v220, v220
	v_exp_f32_e32 v221, v221
	v_exp_f32_e32 v222, v222
	v_exp_f32_e32 v223, v223
	v_add_f32_e32 v220, 1.0, v220
	v_add_f32_e32 v221, 1.0, v221
	v_add_f32_e32 v222, 1.0, v222
	v_add_f32_e32 v223, 1.0, v223
	v_rcp_f32_e32 v224, v220
	v_rcp_f32_e32 v225, v221
	v_rcp_f32_e32 v226, v222
	v_rcp_f32_e32 v227, v223
	v_fma_f32 v228, -v220, v224, 1.0
	v_fma_f32 v229, -v221, v225, 1.0
	v_fma_f32 v230, -v222, v226, 1.0
	v_fma_f32 v231, -v223, v227, 1.0
	v_fmac_f32_e32 v224, v228, v224
	v_fmac_f32_e32 v225, v229, v225
	v_fmac_f32_e32 v226, v230, v226
	v_fmac_f32_e32 v227, v231, v227
	v_div_fixup_f32 v224, v224, v220, 1.0
	v_div_fixup_f32 v225, v225, v221, 1.0
	v_div_fixup_f32 v226, v226, v222, 1.0
	v_div_fixup_f32 v227, v227, v223, 1.0
	v_cvt_pk_bf16_f32 v137, v224, v225
	v_cvt_pk_bf16_f32 v136, v226, v227
	v_mul_f32_e32 v220, 0xbfb8aa3b, v76
	v_mul_f32_e32 v221, 0xbfb8aa3b, v77
	v_mul_f32_e32 v222, 0xbfb8aa3b, v74
	v_mul_f32_e32 v223, 0xbfb8aa3b, v75
	v_exp_f32_e32 v220, v220
	v_exp_f32_e32 v221, v221
	v_exp_f32_e32 v222, v222
	v_exp_f32_e32 v223, v223
	v_add_f32_e32 v220, 1.0, v220
	v_add_f32_e32 v221, 1.0, v221
	v_add_f32_e32 v222, 1.0, v222
	v_add_f32_e32 v223, 1.0, v223
	v_rcp_f32_e32 v224, v220
	v_rcp_f32_e32 v225, v221
	v_rcp_f32_e32 v226, v222
	v_rcp_f32_e32 v227, v223
	v_fma_f32 v228, -v220, v224, 1.0
	v_fma_f32 v229, -v221, v225, 1.0
	v_fma_f32 v230, -v222, v226, 1.0
	v_fma_f32 v231, -v223, v227, 1.0
	v_fmac_f32_e32 v224, v228, v224
	v_fmac_f32_e32 v225, v229, v225
	v_fmac_f32_e32 v226, v230, v226
	v_fmac_f32_e32 v227, v231, v227
	v_div_fixup_f32 v224, v224, v220, 1.0
	v_div_fixup_f32 v225, v225, v221, 1.0
	v_div_fixup_f32 v226, v226, v222, 1.0
	v_div_fixup_f32 v227, v227, v223, 1.0
	v_cvt_pk_bf16_f32 v135, v224, v225
	v_cvt_pk_bf16_f32 v134, v226, v227
	v_mul_f32_e32 v220, 0xbfb8aa3b, v72
	v_mul_f32_e32 v221, 0xbfb8aa3b, v73
	v_mul_f32_e32 v222, 0xbfb8aa3b, v70
	v_mul_f32_e32 v223, 0xbfb8aa3b, v71
	v_exp_f32_e32 v220, v220
	v_exp_f32_e32 v221, v221
	v_exp_f32_e32 v222, v222
	v_exp_f32_e32 v223, v223
	v_add_f32_e32 v220, 1.0, v220
	v_add_f32_e32 v221, 1.0, v221
	v_add_f32_e32 v222, 1.0, v222
	v_add_f32_e32 v223, 1.0, v223
	v_rcp_f32_e32 v224, v220
	v_rcp_f32_e32 v225, v221
	v_rcp_f32_e32 v226, v222
	v_rcp_f32_e32 v227, v223
	v_fma_f32 v228, -v220, v224, 1.0
	v_fma_f32 v229, -v221, v225, 1.0
	v_fma_f32 v230, -v222, v226, 1.0
	v_fma_f32 v231, -v223, v227, 1.0
	v_fmac_f32_e32 v224, v228, v224
	v_fmac_f32_e32 v225, v229, v225
	v_fmac_f32_e32 v226, v230, v226
	v_fmac_f32_e32 v227, v231, v227
	v_div_fixup_f32 v224, v224, v220, 1.0
	v_div_fixup_f32 v225, v225, v221, 1.0
	v_div_fixup_f32 v226, v226, v222, 1.0
	v_div_fixup_f32 v227, v227, v223, 1.0
	v_cvt_pk_bf16_f32 v133, v224, v225
	v_cvt_pk_bf16_f32 v132, v226, v227
	v_mul_f32_e32 v220, 0xbfb8aa3b, v68
	v_mul_f32_e32 v221, 0xbfb8aa3b, v69
	v_mul_f32_e32 v222, 0xbfb8aa3b, v66
	v_mul_f32_e32 v223, 0xbfb8aa3b, v67
	v_exp_f32_e32 v220, v220
	v_exp_f32_e32 v221, v221
	v_exp_f32_e32 v222, v222
	v_exp_f32_e32 v223, v223
	v_add_f32_e32 v220, 1.0, v220
	v_add_f32_e32 v221, 1.0, v221
	v_add_f32_e32 v222, 1.0, v222
	v_add_f32_e32 v223, 1.0, v223
	v_rcp_f32_e32 v224, v220
	v_rcp_f32_e32 v225, v221
	v_rcp_f32_e32 v226, v222
	v_rcp_f32_e32 v227, v223
	v_fma_f32 v228, -v220, v224, 1.0
	v_fma_f32 v229, -v221, v225, 1.0
	v_fma_f32 v230, -v222, v226, 1.0
	v_fma_f32 v231, -v223, v227, 1.0
	v_fmac_f32_e32 v224, v228, v224
	v_fmac_f32_e32 v225, v229, v225
	v_fmac_f32_e32 v226, v230, v226
	v_fmac_f32_e32 v227, v231, v227
	v_div_fixup_f32 v224, v224, v220, 1.0
	v_div_fixup_f32 v225, v225, v221, 1.0
	v_div_fixup_f32 v226, v226, v222, 1.0
	v_div_fixup_f32 v227, v227, v223, 1.0
	v_cvt_pk_bf16_f32 v131, v224, v225
	v_cvt_pk_bf16_f32 v130, v226, v227
	v_mul_f32_e32 v220, 0xbfb8aa3b, v64
	v_mul_f32_e32 v221, 0xbfb8aa3b, v65
	v_mul_f32_e32 v222, 0xbfb8aa3b, v62
	v_mul_f32_e32 v223, 0xbfb8aa3b, v63
	v_exp_f32_e32 v220, v220
	v_exp_f32_e32 v221, v221
	v_exp_f32_e32 v222, v222
	v_exp_f32_e32 v223, v223
	v_add_f32_e32 v220, 1.0, v220
	v_add_f32_e32 v221, 1.0, v221
	v_add_f32_e32 v222, 1.0, v222
	v_add_f32_e32 v223, 1.0, v223
	v_rcp_f32_e32 v224, v220
	v_rcp_f32_e32 v225, v221
	v_rcp_f32_e32 v226, v222
	v_rcp_f32_e32 v227, v223
	v_fma_f32 v228, -v220, v224, 1.0
	v_fma_f32 v229, -v221, v225, 1.0
	v_fma_f32 v230, -v222, v226, 1.0
	v_fma_f32 v231, -v223, v227, 1.0
	v_fmac_f32_e32 v224, v228, v224
	v_fmac_f32_e32 v225, v229, v225
	v_fmac_f32_e32 v226, v230, v226
	v_fmac_f32_e32 v227, v231, v227
	v_div_fixup_f32 v224, v224, v220, 1.0
	v_div_fixup_f32 v225, v225, v221, 1.0
	v_div_fixup_f32 v226, v226, v222, 1.0
	v_div_fixup_f32 v227, v227, v223, 1.0
	v_cvt_pk_bf16_f32 v129, v224, v225
	v_cvt_pk_bf16_f32 v128, v226, v227
	v_mul_f32_e32 v220, 0xbfb8aa3b, v60
	v_mul_f32_e32 v221, 0xbfb8aa3b, v61
	v_mul_f32_e32 v222, 0xbfb8aa3b, v58
	v_mul_f32_e32 v223, 0xbfb8aa3b, v59
	v_exp_f32_e32 v220, v220
	v_exp_f32_e32 v221, v221
	v_exp_f32_e32 v222, v222
	v_exp_f32_e32 v223, v223
	v_add_f32_e32 v220, 1.0, v220
	v_add_f32_e32 v221, 1.0, v221
	v_add_f32_e32 v222, 1.0, v222
	v_add_f32_e32 v223, 1.0, v223
	v_rcp_f32_e32 v224, v220
	v_rcp_f32_e32 v225, v221
	v_rcp_f32_e32 v226, v222
	v_rcp_f32_e32 v227, v223
	v_fma_f32 v228, -v220, v224, 1.0
	v_fma_f32 v229, -v221, v225, 1.0
	v_fma_f32 v230, -v222, v226, 1.0
	v_fma_f32 v231, -v223, v227, 1.0
	v_fmac_f32_e32 v224, v228, v224
	v_fmac_f32_e32 v225, v229, v225
	v_fmac_f32_e32 v226, v230, v226
	v_fmac_f32_e32 v227, v231, v227
	v_div_fixup_f32 v224, v224, v220, 1.0
	v_div_fixup_f32 v225, v225, v221, 1.0
	v_div_fixup_f32 v226, v226, v222, 1.0
	v_div_fixup_f32 v227, v227, v223, 1.0
	v_cvt_pk_bf16_f32 v127, v224, v225
	v_cvt_pk_bf16_f32 v126, v226, v227
	v_mul_f32_e32 v220, 0xbfb8aa3b, v56
	v_mul_f32_e32 v221, 0xbfb8aa3b, v57
	v_mul_f32_e32 v222, 0xbfb8aa3b, v54
	v_mul_f32_e32 v223, 0xbfb8aa3b, v55
	v_exp_f32_e32 v220, v220
	v_exp_f32_e32 v221, v221
	v_exp_f32_e32 v222, v222
	v_exp_f32_e32 v223, v223
	v_add_f32_e32 v220, 1.0, v220
	v_add_f32_e32 v221, 1.0, v221
	v_add_f32_e32 v222, 1.0, v222
	v_add_f32_e32 v223, 1.0, v223
	v_rcp_f32_e32 v224, v220
	v_rcp_f32_e32 v225, v221
	v_rcp_f32_e32 v226, v222
	v_rcp_f32_e32 v227, v223
	v_fma_f32 v228, -v220, v224, 1.0
	v_fma_f32 v229, -v221, v225, 1.0
	v_fma_f32 v230, -v222, v226, 1.0
	v_fma_f32 v231, -v223, v227, 1.0
	v_fmac_f32_e32 v224, v228, v224
	v_fmac_f32_e32 v225, v229, v225
	v_fmac_f32_e32 v226, v230, v226
	v_fmac_f32_e32 v227, v231, v227
	v_div_fixup_f32 v224, v224, v220, 1.0
	v_div_fixup_f32 v225, v225, v221, 1.0
	v_div_fixup_f32 v226, v226, v222, 1.0
	v_div_fixup_f32 v227, v227, v223, 1.0
	v_cvt_pk_bf16_f32 v125, v224, v225
	v_cvt_pk_bf16_f32 v124, v226, v227
	v_mul_f32_e32 v220, 0xbfb8aa3b, v52
	v_mul_f32_e32 v221, 0xbfb8aa3b, v53
	v_mul_f32_e32 v222, 0xbfb8aa3b, v50
	v_mul_f32_e32 v223, 0xbfb8aa3b, v51
	v_exp_f32_e32 v220, v220
	v_exp_f32_e32 v221, v221
	v_exp_f32_e32 v222, v222
	v_exp_f32_e32 v223, v223
	v_add_f32_e32 v220, 1.0, v220
	v_add_f32_e32 v221, 1.0, v221
	v_add_f32_e32 v222, 1.0, v222
	v_add_f32_e32 v223, 1.0, v223
	v_rcp_f32_e32 v224, v220
	v_rcp_f32_e32 v225, v221
	v_rcp_f32_e32 v226, v222
	v_rcp_f32_e32 v227, v223
	v_fma_f32 v228, -v220, v224, 1.0
	v_fma_f32 v229, -v221, v225, 1.0
	v_fma_f32 v230, -v222, v226, 1.0
	v_fma_f32 v231, -v223, v227, 1.0
	v_fmac_f32_e32 v224, v228, v224
	v_fmac_f32_e32 v225, v229, v225
	v_fmac_f32_e32 v226, v230, v226
	v_fmac_f32_e32 v227, v231, v227
	v_div_fixup_f32 v224, v224, v220, 1.0
	v_div_fixup_f32 v225, v225, v221, 1.0
	v_div_fixup_f32 v226, v226, v222, 1.0
	v_div_fixup_f32 v227, v227, v223, 1.0
	v_cvt_pk_bf16_f32 v123, v224, v225
	v_cvt_pk_bf16_f32 v122, v226, v227
	v_mul_f32_e32 v220, 0xbfb8aa3b, v48
	v_mul_f32_e32 v221, 0xbfb8aa3b, v49
	v_mul_f32_e32 v222, 0xbfb8aa3b, v46
	v_mul_f32_e32 v223, 0xbfb8aa3b, v47
	v_exp_f32_e32 v220, v220
	v_exp_f32_e32 v221, v221
	v_exp_f32_e32 v222, v222
	v_exp_f32_e32 v223, v223
	v_add_f32_e32 v220, 1.0, v220
	v_add_f32_e32 v221, 1.0, v221
	v_add_f32_e32 v222, 1.0, v222
	v_add_f32_e32 v223, 1.0, v223
	v_rcp_f32_e32 v224, v220
	v_rcp_f32_e32 v225, v221
	v_rcp_f32_e32 v226, v222
	v_rcp_f32_e32 v227, v223
	v_fma_f32 v228, -v220, v224, 1.0
	v_fma_f32 v229, -v221, v225, 1.0
	v_fma_f32 v230, -v222, v226, 1.0
	v_fma_f32 v231, -v223, v227, 1.0
	v_fmac_f32_e32 v224, v228, v224
	v_fmac_f32_e32 v225, v229, v225
	v_fmac_f32_e32 v226, v230, v226
	v_fmac_f32_e32 v227, v231, v227
	v_div_fixup_f32 v224, v224, v220, 1.0
	v_div_fixup_f32 v225, v225, v221, 1.0
	v_div_fixup_f32 v226, v226, v222, 1.0
	v_div_fixup_f32 v227, v227, v223, 1.0
	v_cvt_pk_bf16_f32 v121, v224, v225
	v_cvt_pk_bf16_f32 v120, v226, v227
	v_mul_f32_e32 v220, 0xbfb8aa3b, v44
	v_mul_f32_e32 v221, 0xbfb8aa3b, v45
	v_mul_f32_e32 v222, 0xbfb8aa3b, v42
	v_mul_f32_e32 v223, 0xbfb8aa3b, v43
	v_exp_f32_e32 v220, v220
	v_exp_f32_e32 v221, v221
	v_exp_f32_e32 v222, v222
	v_exp_f32_e32 v223, v223
	v_add_f32_e32 v220, 1.0, v220
	v_add_f32_e32 v221, 1.0, v221
	v_add_f32_e32 v222, 1.0, v222
	v_add_f32_e32 v223, 1.0, v223
	v_rcp_f32_e32 v224, v220
	v_rcp_f32_e32 v225, v221
	v_rcp_f32_e32 v226, v222
	v_rcp_f32_e32 v227, v223
	v_fma_f32 v228, -v220, v224, 1.0
	v_fma_f32 v229, -v221, v225, 1.0
	v_fma_f32 v230, -v222, v226, 1.0
	v_fma_f32 v231, -v223, v227, 1.0
	v_fmac_f32_e32 v224, v228, v224
	v_fmac_f32_e32 v225, v229, v225
	v_fmac_f32_e32 v226, v230, v226
	v_fmac_f32_e32 v227, v231, v227
	v_div_fixup_f32 v224, v224, v220, 1.0
	v_div_fixup_f32 v225, v225, v221, 1.0
	v_div_fixup_f32 v226, v226, v222, 1.0
	v_div_fixup_f32 v227, v227, v223, 1.0
	v_cvt_pk_bf16_f32 v119, v224, v225
	v_cvt_pk_bf16_f32 v118, v226, v227
	v_mul_f32_e32 v220, 0xbfb8aa3b, v40
	v_mul_f32_e32 v221, 0xbfb8aa3b, v41
	v_mul_f32_e32 v222, 0xbfb8aa3b, v38
	v_mul_f32_e32 v223, 0xbfb8aa3b, v39
	v_exp_f32_e32 v220, v220
	v_exp_f32_e32 v221, v221
	v_exp_f32_e32 v222, v222
	v_exp_f32_e32 v223, v223
	v_add_f32_e32 v220, 1.0, v220
	v_add_f32_e32 v221, 1.0, v221
	v_add_f32_e32 v222, 1.0, v222
	v_add_f32_e32 v223, 1.0, v223
	v_rcp_f32_e32 v224, v220
	v_rcp_f32_e32 v225, v221
	v_rcp_f32_e32 v226, v222
	v_rcp_f32_e32 v227, v223
	v_fma_f32 v228, -v220, v224, 1.0
	v_fma_f32 v229, -v221, v225, 1.0
	v_fma_f32 v230, -v222, v226, 1.0
	v_fma_f32 v231, -v223, v227, 1.0
	v_fmac_f32_e32 v224, v228, v224
	v_fmac_f32_e32 v225, v229, v225
	v_fmac_f32_e32 v226, v230, v226
	v_fmac_f32_e32 v227, v231, v227
	v_div_fixup_f32 v224, v224, v220, 1.0
	v_div_fixup_f32 v225, v225, v221, 1.0
	v_div_fixup_f32 v226, v226, v222, 1.0
	v_div_fixup_f32 v227, v227, v223, 1.0
	v_cvt_pk_bf16_f32 v117, v224, v225
	v_cvt_pk_bf16_f32 v116, v226, v227
	v_mul_f32_e32 v220, 0xbfb8aa3b, v36
	v_mul_f32_e32 v221, 0xbfb8aa3b, v37
	v_mul_f32_e32 v222, 0xbfb8aa3b, v34
	v_mul_f32_e32 v223, 0xbfb8aa3b, v35
	v_exp_f32_e32 v220, v220
	v_exp_f32_e32 v221, v221
	v_exp_f32_e32 v222, v222
	v_exp_f32_e32 v223, v223
	v_add_f32_e32 v220, 1.0, v220
	v_add_f32_e32 v221, 1.0, v221
	v_add_f32_e32 v222, 1.0, v222
	v_add_f32_e32 v223, 1.0, v223
	v_rcp_f32_e32 v224, v220
	v_rcp_f32_e32 v225, v221
	v_rcp_f32_e32 v226, v222
	v_rcp_f32_e32 v227, v223
	v_fma_f32 v228, -v220, v224, 1.0
	v_fma_f32 v229, -v221, v225, 1.0
	v_fma_f32 v230, -v222, v226, 1.0
	v_fma_f32 v231, -v223, v227, 1.0
	v_fmac_f32_e32 v224, v228, v224
	v_fmac_f32_e32 v225, v229, v225
	v_fmac_f32_e32 v226, v230, v226
	v_fmac_f32_e32 v227, v231, v227
	v_div_fixup_f32 v224, v224, v220, 1.0
	v_div_fixup_f32 v225, v225, v221, 1.0
	v_div_fixup_f32 v226, v226, v222, 1.0
	v_div_fixup_f32 v227, v227, v223, 1.0
	v_cvt_pk_bf16_f32 v115, v224, v225
	v_cvt_pk_bf16_f32 v114, v226, v227
	v_mul_f32_e32 v220, 0xbfb8aa3b, v32
	v_mul_f32_e32 v221, 0xbfb8aa3b, v33
	v_mul_f32_e32 v222, 0xbfb8aa3b, v30
	v_mul_f32_e32 v223, 0xbfb8aa3b, v31
	v_exp_f32_e32 v220, v220
	v_exp_f32_e32 v221, v221
	v_exp_f32_e32 v222, v222
	v_exp_f32_e32 v223, v223
	v_add_f32_e32 v220, 1.0, v220
	v_add_f32_e32 v221, 1.0, v221
	v_add_f32_e32 v222, 1.0, v222
	v_add_f32_e32 v223, 1.0, v223
	v_rcp_f32_e32 v224, v220
	v_rcp_f32_e32 v225, v221
	v_rcp_f32_e32 v226, v222
	v_rcp_f32_e32 v227, v223
	v_fma_f32 v228, -v220, v224, 1.0
	v_fma_f32 v229, -v221, v225, 1.0
	v_fma_f32 v230, -v222, v226, 1.0
	v_fma_f32 v231, -v223, v227, 1.0
	v_fmac_f32_e32 v224, v228, v224
	v_fmac_f32_e32 v225, v229, v225
	v_fmac_f32_e32 v226, v230, v226
	v_fmac_f32_e32 v227, v231, v227
	v_div_fixup_f32 v224, v224, v220, 1.0
	v_div_fixup_f32 v225, v225, v221, 1.0
	v_div_fixup_f32 v226, v226, v222, 1.0
	v_div_fixup_f32 v227, v227, v223, 1.0
	v_cvt_pk_bf16_f32 v113, v224, v225
	v_cvt_pk_bf16_f32 v112, v226, v227
	v_mul_f32_e32 v220, 0xbfb8aa3b, v28
	v_mul_f32_e32 v221, 0xbfb8aa3b, v29
	v_mul_f32_e32 v222, 0xbfb8aa3b, v26
	v_mul_f32_e32 v223, 0xbfb8aa3b, v27
	v_exp_f32_e32 v220, v220
	v_exp_f32_e32 v221, v221
	v_exp_f32_e32 v222, v222
	v_exp_f32_e32 v223, v223
	v_add_f32_e32 v220, 1.0, v220
	v_add_f32_e32 v221, 1.0, v221
	v_add_f32_e32 v222, 1.0, v222
	v_add_f32_e32 v223, 1.0, v223
	v_rcp_f32_e32 v224, v220
	v_rcp_f32_e32 v225, v221
	v_rcp_f32_e32 v226, v222
	v_rcp_f32_e32 v227, v223
	v_fma_f32 v228, -v220, v224, 1.0
	v_fma_f32 v229, -v221, v225, 1.0
	v_fma_f32 v230, -v222, v226, 1.0
	v_fma_f32 v231, -v223, v227, 1.0
	v_fmac_f32_e32 v224, v228, v224
	v_fmac_f32_e32 v225, v229, v225
	v_fmac_f32_e32 v226, v230, v226
	v_fmac_f32_e32 v227, v231, v227
	v_div_fixup_f32 v224, v224, v220, 1.0
	v_div_fixup_f32 v225, v225, v221, 1.0
	v_div_fixup_f32 v226, v226, v222, 1.0
	v_div_fixup_f32 v227, v227, v223, 1.0
	v_cvt_pk_bf16_f32 v111, v224, v225
	v_cvt_pk_bf16_f32 v110, v226, v227
	v_mul_f32_e32 v220, 0xbfb8aa3b, v24
	v_mul_f32_e32 v221, 0xbfb8aa3b, v25
	v_mul_f32_e32 v222, 0xbfb8aa3b, v22
	v_mul_f32_e32 v223, 0xbfb8aa3b, v23
	v_exp_f32_e32 v220, v220
	v_exp_f32_e32 v221, v221
	v_exp_f32_e32 v222, v222
	v_exp_f32_e32 v223, v223
	v_add_f32_e32 v220, 1.0, v220
	v_add_f32_e32 v221, 1.0, v221
	v_add_f32_e32 v222, 1.0, v222
	v_add_f32_e32 v223, 1.0, v223
	v_rcp_f32_e32 v224, v220
	v_rcp_f32_e32 v225, v221
	v_rcp_f32_e32 v226, v222
	v_rcp_f32_e32 v227, v223
	v_fma_f32 v228, -v220, v224, 1.0
	v_fma_f32 v229, -v221, v225, 1.0
	v_fma_f32 v230, -v222, v226, 1.0
	v_fma_f32 v231, -v223, v227, 1.0
	v_fmac_f32_e32 v224, v228, v224
	v_fmac_f32_e32 v225, v229, v225
	v_fmac_f32_e32 v226, v230, v226
	v_fmac_f32_e32 v227, v231, v227
	v_div_fixup_f32 v224, v224, v220, 1.0
	v_div_fixup_f32 v225, v225, v221, 1.0
	v_div_fixup_f32 v226, v226, v222, 1.0
	v_div_fixup_f32 v227, v227, v223, 1.0
	v_cvt_pk_bf16_f32 v109, v224, v225
	v_cvt_pk_bf16_f32 v108, v226, v227
	v_mul_f32_e32 v220, 0xbfb8aa3b, v20
	v_mul_f32_e32 v221, 0xbfb8aa3b, v21
	v_mul_f32_e32 v222, 0xbfb8aa3b, v18
	v_mul_f32_e32 v223, 0xbfb8aa3b, v19
	v_exp_f32_e32 v220, v220
	v_exp_f32_e32 v221, v221
	v_exp_f32_e32 v222, v222
	v_exp_f32_e32 v223, v223
	v_add_f32_e32 v220, 1.0, v220
	v_add_f32_e32 v221, 1.0, v221
	v_add_f32_e32 v222, 1.0, v222
	v_add_f32_e32 v223, 1.0, v223
	v_rcp_f32_e32 v224, v220
	v_rcp_f32_e32 v225, v221
	v_rcp_f32_e32 v226, v222
	v_rcp_f32_e32 v227, v223
	v_fma_f32 v228, -v220, v224, 1.0
	v_fma_f32 v229, -v221, v225, 1.0
	v_fma_f32 v230, -v222, v226, 1.0
	v_fma_f32 v231, -v223, v227, 1.0
	v_fmac_f32_e32 v224, v228, v224
	v_fmac_f32_e32 v225, v229, v225
	v_fmac_f32_e32 v226, v230, v226
	v_fmac_f32_e32 v227, v231, v227
	v_div_fixup_f32 v224, v224, v220, 1.0
	v_div_fixup_f32 v225, v225, v221, 1.0
	v_div_fixup_f32 v226, v226, v222, 1.0
	v_div_fixup_f32 v227, v227, v223, 1.0
	v_cvt_pk_bf16_f32 v107, v224, v225
	v_cvt_pk_bf16_f32 v106, v226, v227
	v_mul_f32_e32 v220, 0xbfb8aa3b, v16
	v_mul_f32_e32 v221, 0xbfb8aa3b, v17
	v_mul_f32_e32 v222, 0xbfb8aa3b, v14
	v_mul_f32_e32 v223, 0xbfb8aa3b, v15
	v_exp_f32_e32 v220, v220
	v_exp_f32_e32 v221, v221
	v_exp_f32_e32 v222, v222
	v_exp_f32_e32 v223, v223
	v_add_f32_e32 v220, 1.0, v220
	v_add_f32_e32 v221, 1.0, v221
	v_add_f32_e32 v222, 1.0, v222
	v_add_f32_e32 v223, 1.0, v223
	v_rcp_f32_e32 v224, v220
	v_rcp_f32_e32 v225, v221
	v_rcp_f32_e32 v226, v222
	v_rcp_f32_e32 v227, v223
	v_fma_f32 v228, -v220, v224, 1.0
	v_fma_f32 v229, -v221, v225, 1.0
	v_fma_f32 v230, -v222, v226, 1.0
	v_fma_f32 v231, -v223, v227, 1.0
	v_fmac_f32_e32 v224, v228, v224
	v_fmac_f32_e32 v225, v229, v225
	v_fmac_f32_e32 v226, v230, v226
	v_fmac_f32_e32 v227, v231, v227
	v_div_fixup_f32 v224, v224, v220, 1.0
	v_div_fixup_f32 v225, v225, v221, 1.0
	v_div_fixup_f32 v226, v226, v222, 1.0
	v_div_fixup_f32 v227, v227, v223, 1.0
	v_cvt_pk_bf16_f32 v105, v224, v225
	v_cvt_pk_bf16_f32 v104, v226, v227
	v_mul_f32_e32 v220, 0xbfb8aa3b, v12
	v_mul_f32_e32 v221, 0xbfb8aa3b, v13
	v_mul_f32_e32 v222, 0xbfb8aa3b, v10
	v_mul_f32_e32 v223, 0xbfb8aa3b, v11
	v_exp_f32_e32 v220, v220
	v_exp_f32_e32 v221, v221
	v_exp_f32_e32 v222, v222
	v_exp_f32_e32 v223, v223
	v_add_f32_e32 v220, 1.0, v220
	v_add_f32_e32 v221, 1.0, v221
	v_add_f32_e32 v222, 1.0, v222
	v_add_f32_e32 v223, 1.0, v223
	v_rcp_f32_e32 v224, v220
	v_rcp_f32_e32 v225, v221
	v_rcp_f32_e32 v226, v222
	v_rcp_f32_e32 v227, v223
	v_fma_f32 v228, -v220, v224, 1.0
	v_fma_f32 v229, -v221, v225, 1.0
	v_fma_f32 v230, -v222, v226, 1.0
	v_fma_f32 v231, -v223, v227, 1.0
	v_fmac_f32_e32 v224, v228, v224
	v_fmac_f32_e32 v225, v229, v225
	v_fmac_f32_e32 v226, v230, v226
	v_fmac_f32_e32 v227, v231, v227
	v_div_fixup_f32 v224, v224, v220, 1.0
	v_div_fixup_f32 v225, v225, v221, 1.0
	v_div_fixup_f32 v226, v226, v222, 1.0
	v_div_fixup_f32 v227, v227, v223, 1.0
	v_cvt_pk_bf16_f32 v103, v224, v225
	v_cvt_pk_bf16_f32 v102, v226, v227
	v_mul_f32_e32 v220, 0xbfb8aa3b, v8
	v_mul_f32_e32 v221, 0xbfb8aa3b, v9
	v_mul_f32_e32 v222, 0xbfb8aa3b, v6
	v_mul_f32_e32 v223, 0xbfb8aa3b, v7
	v_exp_f32_e32 v220, v220
	v_exp_f32_e32 v221, v221
	v_exp_f32_e32 v222, v222
	v_exp_f32_e32 v223, v223
	v_add_f32_e32 v220, 1.0, v220
	v_add_f32_e32 v221, 1.0, v221
	v_add_f32_e32 v222, 1.0, v222
	v_add_f32_e32 v223, 1.0, v223
	v_rcp_f32_e32 v224, v220
	v_rcp_f32_e32 v225, v221
	v_rcp_f32_e32 v226, v222
	v_rcp_f32_e32 v227, v223
	v_fma_f32 v228, -v220, v224, 1.0
	v_fma_f32 v229, -v221, v225, 1.0
	v_fma_f32 v230, -v222, v226, 1.0
	v_fma_f32 v231, -v223, v227, 1.0
	v_fmac_f32_e32 v224, v228, v224
	v_fmac_f32_e32 v225, v229, v225
	v_fmac_f32_e32 v226, v230, v226
	v_fmac_f32_e32 v227, v231, v227
	v_div_fixup_f32 v224, v224, v220, 1.0
	v_div_fixup_f32 v225, v225, v221, 1.0
	v_div_fixup_f32 v226, v226, v222, 1.0
	v_div_fixup_f32 v227, v227, v223, 1.0
	v_cvt_pk_bf16_f32 v101, v224, v225
	v_cvt_pk_bf16_f32 v100, v226, v227
	v_mul_f32_e32 v220, 0xbfb8aa3b, v4
	v_mul_f32_e32 v221, 0xbfb8aa3b, v5
	v_mul_f32_e32 v222, 0xbfb8aa3b, v2
	v_mul_f32_e32 v223, 0xbfb8aa3b, v3
	v_exp_f32_e32 v220, v220
	v_exp_f32_e32 v221, v221
	v_exp_f32_e32 v222, v222
	v_exp_f32_e32 v223, v223
	v_add_f32_e32 v220, 1.0, v220
	v_add_f32_e32 v221, 1.0, v221
	v_add_f32_e32 v222, 1.0, v222
	v_add_f32_e32 v223, 1.0, v223
	v_rcp_f32_e32 v224, v220
	v_rcp_f32_e32 v225, v221
	v_rcp_f32_e32 v226, v222
	v_rcp_f32_e32 v227, v223
	v_fma_f32 v228, -v220, v224, 1.0
	v_fma_f32 v229, -v221, v225, 1.0
	v_fma_f32 v230, -v222, v226, 1.0
	v_fma_f32 v231, -v223, v227, 1.0
	v_fmac_f32_e32 v224, v228, v224
	v_fmac_f32_e32 v225, v229, v225
	v_fmac_f32_e32 v226, v230, v226
	v_fmac_f32_e32 v227, v231, v227
	v_div_fixup_f32 v224, v224, v220, 1.0
	v_div_fixup_f32 v225, v225, v221, 1.0
	v_div_fixup_f32 v226, v226, v222, 1.0
	v_div_fixup_f32 v227, v227, v223, 1.0
	v_cvt_pk_bf16_f32 v99, v224, v225
	v_cvt_pk_bf16_f32 v98, v226, v227
	s_add_u32 s98, s48, 0x0
	s_addc_u32 s99, s49, 0
	s_add_u32 s100, s44, 0x0
	s_addc_u32 s101, s45, 0
	s_mov_b32 s51, 2
	v_mov_b32_e32 v12, v199
	v_lshrrev_b32_e32 v2, 3, v12
	v_and_b32_e32 v3, 7, v12
	v_bfe_u32 v4, v12, 4, 3
	v_xor_b32_e32 v3, v3, v4
	v_lshlrev_b32_e32 v3, 4, v3
	v_mul_u32_u24_e32 v2, 0x700, v2
	v_add_u32_e32 v220, v2, v3
	v_add_u32_e32 v221, 0xe000, v220
	v_add_u32_e32 v222, 0x1c000, v220
	v_add_u32_e32 v223, 0x2a000, v220
	v_lshlrev_b32_e32 v4, 4, v12
	v_and_b32_e32 v5, 31, v12
	v_bfe_u32 v6, v12, 5, 1
	v_bfe_u32 v7, v12, 1, 3
	v_xor_b32_e32 v6, v6, v7
	v_lshlrev_b32_e32 v226, 4, v6
	v_lshlrev_b32_e32 v5, 7, v5
	v_bfe_u32 v8, v12, 7, 1
	v_bfe_u32 v9, v12, 6, 1
	v_lshl_or_b32 v224, v8, 13, v5
	v_lshl_or_b32 v225, v9, 13, v5
	v_readfirstlane_b32 s52, v4
	s_waitcnt vmcnt(0)
	s_barrier
	s_add_u32 m0, s52, 0x0
	v_mov_b32_e32 v2, 0
	global_load_lds_dwordx4 v220, s[98:99]
	s_add_u32 m0, s52, 0x1000
	v_mov_b32_e32 v3, 0
	global_load_lds_dwordx4 v221, s[98:99]
	s_add_u32 m0, s52, 0x2000
	v_mov_b32_e32 v4, 0
	global_load_lds_dwordx4 v222, s[98:99]
	s_add_u32 m0, s52, 0x3000
	v_mov_b32_e32 v5, 0
	global_load_lds_dwordx4 v223, s[98:99]
	s_add_u32 m0, s52, 0x4000
	v_mov_b32_e32 v6, 0
	global_load_lds_dwordx4 v220, s[100:101]
	s_add_u32 m0, s52, 0x5000
	v_mov_b32_e32 v7, 0
	global_load_lds_dwordx4 v221, s[100:101]
	s_add_u32 m0, s52, 0x6000
	v_mov_b32_e32 v8, 0
	global_load_lds_dwordx4 v222, s[100:101]
	s_add_u32 m0, s52, 0x7000
	v_mov_b32_e32 v9, 0
	global_load_lds_dwordx4 v223, s[100:101]
	s_add_u32 s98, s98, 0x80
	s_addc_u32 s99, s99, 0
	s_add_u32 s100, s100, 0x80
	s_addc_u32 s101, s101, 0
	s_add_u32 m0, s52, 0x8000
	v_mov_b32_e32 v10, 0
	global_load_lds_dwordx4 v220, s[98:99]
	s_add_u32 m0, s52, 0x9000
	v_mov_b32_e32 v11, 0
	global_load_lds_dwordx4 v221, s[98:99]
	s_add_u32 m0, s52, 0xa000
	v_mov_b32_e32 v12, 0
	global_load_lds_dwordx4 v222, s[98:99]
	s_add_u32 m0, s52, 0xb000
	v_mov_b32_e32 v13, 0
	global_load_lds_dwordx4 v223, s[98:99]
	s_add_u32 m0, s52, 0xc000
	v_mov_b32_e32 v14, 0
	global_load_lds_dwordx4 v220, s[100:101]
	s_add_u32 m0, s52, 0xd000
	v_mov_b32_e32 v15, 0
	global_load_lds_dwordx4 v221, s[100:101]
	s_add_u32 m0, s52, 0xe000
	v_mov_b32_e32 v16, 0
	global_load_lds_dwordx4 v222, s[100:101]
	s_add_u32 m0, s52, 0xf000
	v_mov_b32_e32 v17, 0
	global_load_lds_dwordx4 v223, s[100:101]
	s_add_u32 s98, s98, 0x80
	s_addc_u32 s99, s99, 0
	s_add_u32 s100, s100, 0x80
	s_addc_u32 s101, s101, 0
	v_mov_b32_e32 v18, 0
	v_mov_b32_e32 v19, 0
	v_mov_b32_e32 v20, 0
	v_mov_b32_e32 v21, 0
	v_mov_b32_e32 v22, 0
	v_mov_b32_e32 v23, 0
	v_mov_b32_e32 v24, 0
	v_mov_b32_e32 v25, 0
	v_mov_b32_e32 v26, 0
	v_mov_b32_e32 v27, 0
	v_mov_b32_e32 v28, 0
	v_mov_b32_e32 v29, 0
	v_mov_b32_e32 v30, 0
	v_mov_b32_e32 v31, 0
	v_mov_b32_e32 v32, 0
	v_mov_b32_e32 v33, 0
	v_mov_b32_e32 v34, 0
	v_mov_b32_e32 v35, 0
	v_mov_b32_e32 v36, 0
	v_mov_b32_e32 v37, 0
	v_mov_b32_e32 v38, 0
	v_mov_b32_e32 v39, 0
	v_mov_b32_e32 v40, 0
	v_mov_b32_e32 v41, 0
	v_mov_b32_e32 v42, 0
	v_mov_b32_e32 v43, 0
	v_mov_b32_e32 v44, 0
	v_mov_b32_e32 v45, 0
	v_mov_b32_e32 v46, 0
	v_mov_b32_e32 v47, 0
	v_mov_b32_e32 v48, 0
	v_mov_b32_e32 v49, 0
	v_mov_b32_e32 v50, 0
	v_mov_b32_e32 v51, 0
	v_mov_b32_e32 v52, 0
	v_mov_b32_e32 v53, 0
	v_mov_b32_e32 v54, 0
	v_mov_b32_e32 v55, 0
	v_mov_b32_e32 v56, 0
	v_mov_b32_e32 v57, 0
	v_mov_b32_e32 v58, 0
	v_mov_b32_e32 v59, 0
	v_mov_b32_e32 v60, 0
	v_mov_b32_e32 v61, 0
	v_mov_b32_e32 v62, 0
	v_mov_b32_e32 v63, 0
	v_mov_b32_e32 v64, 0
	v_mov_b32_e32 v65, 0
	s_waitcnt vmcnt(8)
	s_barrier
	v_add_u32_e32 v66, v226, v224
	v_add_u32_e32 v70, v226, v225
	ds_read_b128 v[78:81], v66
	ds_read_b128 v[66:69], v66 offset:4096
	ds_read_b128 v[74:77], v70 offset:16384
	ds_read_b128 v[70:73], v70 offset:20480
